# loop-edge rotation: address/counter SALU of GEMM load segments and loop tail hoisted between the last MFMAs of the preceding MFMA segment
# baseline (speedup 1.0000x reference)
.LBB0_216:
	ds_read_b128 v[152:155], v160
	ds_read_b128 v[164:167], v160 offset:1024
	ds_read_b128 v[168:171], v160 offset:2048
	ds_read_b128 v[172:175], v160 offset:3072
	ds_read_b128 v[176:179], v161
	ds_read_b128 v[180:183], v161 offset:1024
	ds_read_b128 v[184:187], v161 offset:2048
	ds_read_b128 v[188:191], v161 offset:3072
	s_add_u32 s20, s0, 0xfff00080
	s_addc_u32 s21, s1, -1
	s_cmp_eq_u32 s30, 60
	s_cselect_b32 s23, s13, s21
	s_cselect_b32 s22, s24, s20
	s_cselect_b32 s21, s15, s29
	s_cselect_b32 s20, s25, s27
	s_add_i32 m0, s39, 0xc000
	ds_read_b128 v[192:195], v162
	ds_read_b128 v[196:199], v162 offset:1024
	ds_read_b128 v[200:203], v162 offset:2048
	ds_read_b128 v[204:207], v162 offset:3072
	ds_read_b128 v[208:211], v162 offset:4096
	ds_read_b128 v[212:215], v162 offset:5120
	ds_read_b128 v[216:219], v162 offset:6144
	ds_read_b128 v[220:223], v162 offset:7168
	global_load_lds_dwordx4 v140, s[0:1]
	s_add_i32 m0, s39, 0xe000
	s_nop 0
	global_load_lds_dwordx4 v142, s[0:1]
	s_waitcnt vmcnt(8)
	s_waitcnt lgkmcnt(0)
	s_barrier
	v_mfma_f32_16x16x32_bf16 v[126:129], v[152:155], v[192:195], v[126:129]
	v_mfma_f32_16x16x32_bf16 v[126:129], v[164:167], v[196:199], v[126:129]
	v_mfma_f32_16x16x32_bf16 v[122:125], v[168:171], v[192:195], v[122:125]
	v_mfma_f32_16x16x32_bf16 v[122:125], v[172:175], v[196:199], v[122:125]
	v_mfma_f32_16x16x32_bf16 v[114:117], v[152:155], v[200:203], v[114:117]
	v_mfma_f32_16x16x32_bf16 v[114:117], v[164:167], v[204:207], v[114:117]
	v_mfma_f32_16x16x32_bf16 v[106:109], v[168:171], v[200:203], v[106:109]
	v_mfma_f32_16x16x32_bf16 v[106:109], v[172:175], v[204:207], v[106:109]
	v_mfma_f32_16x16x32_bf16 v[98:101], v[152:155], v[208:211], v[98:101]
	v_mfma_f32_16x16x32_bf16 v[98:101], v[164:167], v[212:215], v[98:101]
	v_mfma_f32_16x16x32_bf16 v[90:93], v[168:171], v[208:211], v[90:93]
	v_mfma_f32_16x16x32_bf16 v[90:93], v[172:175], v[212:215], v[90:93]
	v_mfma_f32_16x16x32_bf16 v[82:85], v[152:155], v[216:219], v[82:85]
	v_mfma_f32_16x16x32_bf16 v[82:85], v[164:167], v[220:223], v[82:85]
	v_mfma_f32_16x16x32_bf16 v[74:77], v[168:171], v[216:219], v[74:77]
	v_mfma_f32_16x16x32_bf16 v[74:77], v[172:175], v[220:223], v[74:77]
	v_mfma_f32_16x16x32_bf16 v[118:121], v[176:179], v[192:195], v[118:121]
	v_mfma_f32_16x16x32_bf16 v[118:121], v[180:183], v[196:199], v[118:121]
	v_mfma_f32_16x16x32_bf16 v[110:113], v[184:187], v[192:195], v[110:113]
	v_mfma_f32_16x16x32_bf16 v[110:113], v[188:191], v[196:199], v[110:113]
	v_mfma_f32_16x16x32_bf16 v[102:105], v[176:179], v[200:203], v[102:105]
	v_mfma_f32_16x16x32_bf16 v[102:105], v[180:183], v[204:207], v[102:105]
	v_mfma_f32_16x16x32_bf16 v[94:97], v[184:187], v[200:203], v[94:97]
	v_mfma_f32_16x16x32_bf16 v[94:97], v[188:191], v[204:207], v[94:97]
	v_mfma_f32_16x16x32_bf16 v[86:89], v[176:179], v[208:211], v[86:89]
	v_mfma_f32_16x16x32_bf16 v[86:89], v[180:183], v[212:215], v[86:89]
	v_mfma_f32_16x16x32_bf16 v[78:81], v[184:187], v[208:211], v[78:81]
	v_mfma_f32_16x16x32_bf16 v[78:81], v[188:191], v[212:215], v[78:81]
	v_mfma_f32_16x16x32_bf16 v[70:73], v[176:179], v[216:219], v[70:73]
	v_mfma_f32_16x16x32_bf16 v[70:73], v[180:183], v[220:223], v[70:73]
	s_add_i32 s31, s49, s38
	s_mov_b32 m0, s31
	v_mfma_f32_16x16x32_bf16 v[66:69], v[184:187], v[216:219], v[66:69]
	v_mfma_f32_16x16x32_bf16 v[66:69], v[188:191], v[220:223], v[66:69]
	s_barrier
	ds_read_b128 v[192:195], v162 offset:16384
	ds_read_b128 v[196:199], v162 offset:17408
	ds_read_b128 v[200:203], v162 offset:18432
	ds_read_b128 v[204:207], v162 offset:19456
	ds_read_b128 v[208:211], v162 offset:20480
	ds_read_b128 v[212:215], v162 offset:21504
	ds_read_b128 v[216:219], v162 offset:22528
	ds_read_b128 v[220:223], v162 offset:23552
	global_load_lds_dwordx4 v132, s[20:21]
	s_add_i32 m0, s31, 0x2000
	s_add_u32 s34, s20, 0x100000
	s_addc_u32 s35, s21, 0
	s_add_i32 s31, s50, s38
	global_load_lds_dwordx4 v136, s[20:21]
	s_mov_b32 m0, s31
	global_load_lds_dwordx4 v132, s[34:35]
	s_add_i32 m0, s31, 0x2000
	s_nop 0
	global_load_lds_dwordx4 v136, s[34:35]
	s_mov_b32 m0, s39
	s_nop 0
	global_load_lds_dwordx4 v130, s[22:23]
	s_mov_b32 m0, s40
	s_nop 0
	global_load_lds_dwordx4 v134, s[22:23]
	s_waitcnt vmcnt(8)
	s_waitcnt lgkmcnt(0)
	s_barrier
	v_mfma_f32_16x16x32_bf16 v[62:65], v[152:155], v[192:195], v[62:65]
	v_mfma_f32_16x16x32_bf16 v[62:65], v[164:167], v[196:199], v[62:65]
	v_mfma_f32_16x16x32_bf16 v[58:61], v[168:171], v[192:195], v[58:61]
	v_mfma_f32_16x16x32_bf16 v[58:61], v[172:175], v[196:199], v[58:61]
	v_mfma_f32_16x16x32_bf16 v[46:49], v[152:155], v[200:203], v[46:49]
	v_mfma_f32_16x16x32_bf16 v[46:49], v[164:167], v[204:207], v[46:49]
	v_mfma_f32_16x16x32_bf16 v[42:45], v[168:171], v[200:203], v[42:45]
	v_mfma_f32_16x16x32_bf16 v[42:45], v[172:175], v[204:207], v[42:45]
	v_mfma_f32_16x16x32_bf16 v[30:33], v[152:155], v[208:211], v[30:33]
	v_mfma_f32_16x16x32_bf16 v[30:33], v[164:167], v[212:215], v[30:33]
	v_mfma_f32_16x16x32_bf16 v[26:29], v[168:171], v[208:211], v[26:29]
	v_mfma_f32_16x16x32_bf16 v[26:29], v[172:175], v[212:215], v[26:29]
	v_mfma_f32_16x16x32_bf16 v[14:17], v[152:155], v[216:219], v[14:17]
	v_mfma_f32_16x16x32_bf16 v[14:17], v[164:167], v[220:223], v[14:17]
	v_mfma_f32_16x16x32_bf16 v[10:13], v[168:171], v[216:219], v[10:13]
	v_mfma_f32_16x16x32_bf16 v[10:13], v[172:175], v[220:223], v[10:13]
	v_mfma_f32_16x16x32_bf16 v[54:57], v[176:179], v[192:195], v[54:57]
	v_mfma_f32_16x16x32_bf16 v[54:57], v[180:183], v[196:199], v[54:57]
	v_mfma_f32_16x16x32_bf16 v[50:53], v[184:187], v[192:195], v[50:53]
	v_mfma_f32_16x16x32_bf16 v[50:53], v[188:191], v[196:199], v[50:53]
	v_mfma_f32_16x16x32_bf16 v[38:41], v[176:179], v[200:203], v[38:41]
	v_mfma_f32_16x16x32_bf16 v[38:41], v[180:183], v[204:207], v[38:41]
	v_mfma_f32_16x16x32_bf16 v[34:37], v[184:187], v[200:203], v[34:37]
	v_mfma_f32_16x16x32_bf16 v[34:37], v[188:191], v[204:207], v[34:37]
	s_add_i32 s31, 0, 0x18000
	s_add_i32 s33, 0, 0x1c000
	v_mfma_f32_16x16x32_bf16 v[22:25], v[176:179], v[208:211], v[22:25]
	v_mfma_f32_16x16x32_bf16 v[22:25], v[180:183], v[212:215], v[22:25]
	s_add_u32 s98, s22, 0x80
	s_addc_u32 s99, s23, 0
	v_mfma_f32_16x16x32_bf16 v[18:21], v[184:187], v[208:211], v[18:21]
	v_mfma_f32_16x16x32_bf16 v[18:21], v[188:191], v[212:215], v[18:21]
	s_add_u32 s22, s22, 0x100000
	s_addc_u32 s23, s23, 0
	v_mfma_f32_16x16x32_bf16 v[6:9], v[176:179], v[216:219], v[6:9]
	v_mfma_f32_16x16x32_bf16 v[6:9], v[180:183], v[220:223], v[6:9]
	s_mov_b32 m0, s41
	v_mfma_f32_16x16x32_bf16 v[2:5], v[184:187], v[216:219], v[2:5]
	v_mfma_f32_16x16x32_bf16 v[2:5], v[188:191], v[220:223], v[2:5]
	s_barrier
	ds_read_b128 v[152:155], v246
	ds_read_b128 v[164:167], v246 offset:1024
	ds_read_b128 v[168:171], v246 offset:2048
	ds_read_b128 v[172:175], v246 offset:3072
	ds_read_b128 v[176:179], v247
	ds_read_b128 v[180:183], v247 offset:1024
	ds_read_b128 v[184:187], v247 offset:2048
	ds_read_b128 v[188:191], v247 offset:3072
	ds_read_b128 v[192:195], v162 offset:32768
	ds_read_b128 v[196:199], v162 offset:33792
	ds_read_b128 v[200:203], v162 offset:34816
	ds_read_b128 v[204:207], v162 offset:35840
	ds_read_b128 v[208:211], v162 offset:36864
	ds_read_b128 v[212:215], v162 offset:37888
	ds_read_b128 v[216:219], v162 offset:38912
	ds_read_b128 v[220:223], v162 offset:39936
	global_load_lds_dwordx4 v130, s[22:23]
	s_mov_b32 m0, s42
	s_nop 0
	global_load_lds_dwordx4 v134, s[22:23]
	s_waitcnt vmcnt(8)
	s_waitcnt lgkmcnt(0)
	s_barrier
	v_mfma_f32_16x16x32_bf16 v[126:129], v[152:155], v[192:195], v[126:129]
	v_mfma_f32_16x16x32_bf16 v[126:129], v[164:167], v[196:199], v[126:129]
	v_mfma_f32_16x16x32_bf16 v[122:125], v[168:171], v[192:195], v[122:125]
	v_mfma_f32_16x16x32_bf16 v[122:125], v[172:175], v[196:199], v[122:125]
	v_mfma_f32_16x16x32_bf16 v[114:117], v[152:155], v[200:203], v[114:117]
	v_mfma_f32_16x16x32_bf16 v[114:117], v[164:167], v[204:207], v[114:117]
	v_mfma_f32_16x16x32_bf16 v[106:109], v[168:171], v[200:203], v[106:109]
	v_mfma_f32_16x16x32_bf16 v[106:109], v[172:175], v[204:207], v[106:109]
	v_mfma_f32_16x16x32_bf16 v[98:101], v[152:155], v[208:211], v[98:101]
	v_mfma_f32_16x16x32_bf16 v[98:101], v[164:167], v[212:215], v[98:101]
	v_mfma_f32_16x16x32_bf16 v[90:93], v[168:171], v[208:211], v[90:93]
	v_mfma_f32_16x16x32_bf16 v[90:93], v[172:175], v[212:215], v[90:93]
	v_mfma_f32_16x16x32_bf16 v[82:85], v[152:155], v[216:219], v[82:85]
	v_mfma_f32_16x16x32_bf16 v[82:85], v[164:167], v[220:223], v[82:85]
	v_mfma_f32_16x16x32_bf16 v[74:77], v[168:171], v[216:219], v[74:77]
	v_mfma_f32_16x16x32_bf16 v[74:77], v[172:175], v[220:223], v[74:77]
	v_mfma_f32_16x16x32_bf16 v[118:121], v[176:179], v[192:195], v[118:121]
	v_mfma_f32_16x16x32_bf16 v[118:121], v[180:183], v[196:199], v[118:121]
	v_mfma_f32_16x16x32_bf16 v[110:113], v[184:187], v[192:195], v[110:113]
	v_mfma_f32_16x16x32_bf16 v[110:113], v[188:191], v[196:199], v[110:113]
	v_mfma_f32_16x16x32_bf16 v[102:105], v[176:179], v[200:203], v[102:105]
	v_mfma_f32_16x16x32_bf16 v[102:105], v[180:183], v[204:207], v[102:105]
	v_mfma_f32_16x16x32_bf16 v[94:97], v[184:187], v[200:203], v[94:97]
	v_mfma_f32_16x16x32_bf16 v[94:97], v[188:191], v[204:207], v[94:97]
	v_mfma_f32_16x16x32_bf16 v[86:89], v[176:179], v[208:211], v[86:89]
	v_mfma_f32_16x16x32_bf16 v[86:89], v[180:183], v[212:215], v[86:89]
	v_mfma_f32_16x16x32_bf16 v[78:81], v[184:187], v[208:211], v[78:81]
	v_mfma_f32_16x16x32_bf16 v[78:81], v[188:191], v[212:215], v[78:81]
	s_add_i32 s22, s31, s38
	s_mov_b32 m0, s22
	v_mfma_f32_16x16x32_bf16 v[70:73], v[176:179], v[216:219], v[70:73]
	v_mfma_f32_16x16x32_bf16 v[70:73], v[180:183], v[220:223], v[70:73]
	s_add_u32 s20, s20, 0x80
	s_addc_u32 s21, s21, 0
	v_mfma_f32_16x16x32_bf16 v[66:69], v[184:187], v[216:219], v[66:69]
	v_mfma_f32_16x16x32_bf16 v[66:69], v[188:191], v[220:223], v[66:69]
	s_barrier
	ds_read_b128 v[192:195], v162 offset:49152
	ds_read_b128 v[196:199], v162 offset:50176
	ds_read_b128 v[200:203], v162 offset:51200
	ds_read_b128 v[204:207], v162 offset:52224
	ds_read_b128 v[208:211], v162 offset:53248
	ds_read_b128 v[212:215], v162 offset:54272
	ds_read_b128 v[216:219], v162 offset:55296
	ds_read_b128 v[220:223], v162 offset:56320
	global_load_lds_dwordx4 v132, s[20:21]
	s_add_i32 m0, s22, 0x2000
	s_add_i32 s22, s33, s38
	global_load_lds_dwordx4 v136, s[20:21]
	s_add_u32 s20, s20, 0x100000
	s_addc_u32 s21, s21, 0
	s_mov_b32 m0, s22
	s_nop 0
	global_load_lds_dwordx4 v132, s[20:21]
	s_add_i32 m0, s22, 0x2000
	s_nop 0
	global_load_lds_dwordx4 v136, s[20:21]
	s_mov_b32 m0, s45
	s_nop 0
	global_load_lds_dwordx4 v130, s[98:99]
	s_mov_b32 m0, s46
	s_nop 0
	global_load_lds_dwordx4 v134, s[98:99]
	s_waitcnt vmcnt(8)
	s_waitcnt lgkmcnt(0)
	s_barrier
	v_mfma_f32_16x16x32_bf16 v[62:65], v[152:155], v[192:195], v[62:65]
	v_mfma_f32_16x16x32_bf16 v[62:65], v[164:167], v[196:199], v[62:65]
	v_mfma_f32_16x16x32_bf16 v[58:61], v[168:171], v[192:195], v[58:61]
	v_mfma_f32_16x16x32_bf16 v[58:61], v[172:175], v[196:199], v[58:61]
	v_mfma_f32_16x16x32_bf16 v[46:49], v[152:155], v[200:203], v[46:49]
	v_mfma_f32_16x16x32_bf16 v[46:49], v[164:167], v[204:207], v[46:49]
	v_mfma_f32_16x16x32_bf16 v[42:45], v[168:171], v[200:203], v[42:45]
	v_mfma_f32_16x16x32_bf16 v[42:45], v[172:175], v[204:207], v[42:45]
	v_mfma_f32_16x16x32_bf16 v[30:33], v[152:155], v[208:211], v[30:33]
	v_mfma_f32_16x16x32_bf16 v[30:33], v[164:167], v[212:215], v[30:33]
	v_mfma_f32_16x16x32_bf16 v[26:29], v[168:171], v[208:211], v[26:29]
	v_mfma_f32_16x16x32_bf16 v[26:29], v[172:175], v[212:215], v[26:29]
	v_mfma_f32_16x16x32_bf16 v[14:17], v[152:155], v[216:219], v[14:17]
	v_mfma_f32_16x16x32_bf16 v[14:17], v[164:167], v[220:223], v[14:17]
	v_mfma_f32_16x16x32_bf16 v[10:13], v[168:171], v[216:219], v[10:13]
	v_mfma_f32_16x16x32_bf16 v[10:13], v[172:175], v[220:223], v[10:13]
	v_mfma_f32_16x16x32_bf16 v[54:57], v[176:179], v[192:195], v[54:57]
	v_mfma_f32_16x16x32_bf16 v[54:57], v[180:183], v[196:199], v[54:57]
	v_mfma_f32_16x16x32_bf16 v[50:53], v[184:187], v[192:195], v[50:53]
	v_mfma_f32_16x16x32_bf16 v[50:53], v[188:191], v[196:199], v[50:53]
	v_mfma_f32_16x16x32_bf16 v[38:41], v[176:179], v[200:203], v[38:41]
	v_mfma_f32_16x16x32_bf16 v[38:41], v[180:183], v[204:207], v[38:41]
	v_mfma_f32_16x16x32_bf16 v[34:37], v[184:187], v[200:203], v[34:37]
	v_mfma_f32_16x16x32_bf16 v[34:37], v[188:191], v[204:207], v[34:37]
	v_mfma_f32_16x16x32_bf16 v[22:25], v[176:179], v[208:211], v[22:25]
	v_mfma_f32_16x16x32_bf16 v[22:25], v[180:183], v[212:215], v[22:25]
	s_add_i32 s30, s30, 2
	s_add_u32 s0, s0, 0x100
	v_mfma_f32_16x16x32_bf16 v[18:21], v[184:187], v[208:211], v[18:21]
	v_mfma_f32_16x16x32_bf16 v[18:21], v[188:191], v[212:215], v[18:21]
	s_addc_u32 s1, s1, 0
	s_add_u32 s27, s27, 0x100
	v_mfma_f32_16x16x32_bf16 v[6:9], v[176:179], v[216:219], v[6:9]
	v_mfma_f32_16x16x32_bf16 v[6:9], v[180:183], v[220:223], v[6:9]
	s_addc_u32 s29, s29, 0
	s_cmp_gt_u32 s30, 61
	v_mfma_f32_16x16x32_bf16 v[2:5], v[184:187], v[216:219], v[2:5]
	v_mfma_f32_16x16x32_bf16 v[2:5], v[188:191], v[220:223], v[2:5]
	s_barrier
	s_cbranch_scc0 .LBB0_216
	s_and_b64 vcc, exec, s[10:11]
	s_cbranch_vccz .LBB0_219
	s_barrier

.LBB0_271:
	ds_read_b128 v[26:29], v183
	ds_read_b128 v[30:33], v183 offset:1024
	ds_read_b128 v[18:21], v183 offset:2048
	ds_read_b128 v[22:25], v183 offset:3072
	ds_read_b128 v[10:13], v184
	ds_read_b128 v[14:17], v184 offset:1024
	ds_read_b128 v[2:5], v184 offset:2048
	ds_read_b128 v[6:9], v184 offset:3072
	s_add_u32 s0, s20, 0xfff80080
	s_addc_u32 s1, s21, -1
	s_cmp_eq_u32 s29, 28
	s_cselect_b32 s23, s13, s1
	s_cselect_b32 s22, s25, s0
	s_cselect_b32 s1, s11, s28
	s_cselect_b32 s0, s26, s27
	s_add_i32 m0, s19, 0xc000
	ds_read_b128 v[174:177], v185
	ds_read_b128 v[178:181], v185 offset:1024
	ds_read_b128 v[188:191], v185 offset:2048
	ds_read_b128 v[192:195], v185 offset:3072
	ds_read_b128 v[196:199], v185 offset:4096
	ds_read_b128 v[200:203], v185 offset:5120
	ds_read_b128 v[204:207], v185 offset:6144
	ds_read_b128 v[208:211], v185 offset:7168
	global_load_lds_dwordx4 v162, s[20:21]
	s_add_i32 m0, s19, 0xe000
	s_nop 0
	global_load_lds_dwordx4 v172, s[20:21]
	s_waitcnt vmcnt(8)
	s_waitcnt lgkmcnt(0)
	s_barrier
	v_mfma_f32_16x16x128_f8f6f4 v[158:161], v[26:33], v[174:181], v[158:161]
	v_mfma_f32_16x16x128_f8f6f4 v[154:157], v[18:25], v[174:181], v[154:157]
	v_mfma_f32_16x16x128_f8f6f4 v[146:149], v[26:33], v[188:195], v[146:149]
	v_mfma_f32_16x16x128_f8f6f4 v[138:141], v[18:25], v[188:195], v[138:141]
	v_mfma_f32_16x16x128_f8f6f4 v[130:133], v[26:33], v[196:203], v[130:133]
	v_mfma_f32_16x16x128_f8f6f4 v[122:125], v[18:25], v[196:203], v[122:125]
	v_mfma_f32_16x16x128_f8f6f4 v[114:117], v[26:33], v[204:211], v[114:117]
	v_mfma_f32_16x16x128_f8f6f4 v[106:109], v[18:25], v[204:211], v[106:109]
	v_mfma_f32_16x16x128_f8f6f4 v[150:153], v[10:17], v[174:181], v[150:153]
	v_mfma_f32_16x16x128_f8f6f4 v[142:145], v[2:9], v[174:181], v[142:145]
	v_mfma_f32_16x16x128_f8f6f4 v[134:137], v[10:17], v[188:195], v[134:137]
	v_mfma_f32_16x16x128_f8f6f4 v[126:129], v[2:9], v[188:195], v[126:129]
	v_mfma_f32_16x16x128_f8f6f4 v[118:121], v[10:17], v[196:203], v[118:121]
	v_mfma_f32_16x16x128_f8f6f4 v[110:113], v[2:9], v[196:203], v[110:113]
	s_add_i32 s30, s48, s37
	s_mov_b32 m0, s30
	v_mfma_f32_16x16x128_f8f6f4 v[102:105], v[10:17], v[204:211], v[102:105]
	v_mfma_f32_16x16x128_f8f6f4 v[98:101], v[2:9], v[204:211], v[98:101]
	s_barrier
	ds_read_b128 v[188:191], v185 offset:16384
	ds_read_b128 v[192:195], v185 offset:17408
	ds_read_b128 v[196:199], v185 offset:18432
	ds_read_b128 v[200:203], v185 offset:19456
	ds_read_b128 v[204:207], v185 offset:20480
	ds_read_b128 v[208:211], v185 offset:21504
	ds_read_b128 v[212:215], v185 offset:22528
	ds_read_b128 v[216:219], v185 offset:23552
	global_load_lds_dwordx4 v168, s[0:1]
	s_add_i32 m0, s30, 0x2000
	s_add_u32 s30, s0, 0x80000
	s_addc_u32 s31, s1, 0
	s_add_i32 s33, s49, s37
	global_load_lds_dwordx4 v170, s[0:1]
	s_mov_b32 m0, s33
	global_load_lds_dwordx4 v168, s[30:31]
	s_add_i32 m0, s33, 0x2000
	s_nop 0
	global_load_lds_dwordx4 v170, s[30:31]
	s_mov_b32 m0, s19
	s_nop 0
	global_load_lds_dwordx4 v162, s[22:23]
	s_mov_b32 m0, s38
	s_nop 0
	global_load_lds_dwordx4 v172, s[22:23]
	s_waitcnt vmcnt(8)
	s_waitcnt lgkmcnt(0)
	s_barrier
	v_mfma_f32_16x16x128_f8f6f4 v[94:97], v[26:33], v[188:195], v[94:97]
	v_mfma_f32_16x16x128_f8f6f4 v[90:93], v[18:25], v[188:195], v[90:93]
	v_mfma_f32_16x16x128_f8f6f4 v[78:81], v[26:33], v[196:203], v[78:81]
	v_mfma_f32_16x16x128_f8f6f4 v[74:77], v[18:25], v[196:203], v[74:77]
	v_mfma_f32_16x16x128_f8f6f4 v[62:65], v[26:33], v[204:211], v[62:65]
	v_mfma_f32_16x16x128_f8f6f4 v[58:61], v[18:25], v[204:211], v[58:61]
	v_mfma_f32_16x16x128_f8f6f4 v[46:49], v[26:33], v[212:219], v[46:49]
	v_mfma_f32_16x16x128_f8f6f4 v[42:45], v[18:25], v[212:219], v[42:45]
	s_add_i32 s30, 0, 0x18000
	s_add_i32 s31, 0, 0x1c000
	v_mfma_f32_16x16x128_f8f6f4 v[86:89], v[10:17], v[188:195], v[86:89]
	v_mfma_f32_16x16x128_f8f6f4 v[82:85], v[2:9], v[188:195], v[82:85]
	s_add_u32 s98, s22, 0x80
	s_addc_u32 s99, s23, 0
	v_mfma_f32_16x16x128_f8f6f4 v[70:73], v[10:17], v[196:203], v[70:73]
	v_mfma_f32_16x16x128_f8f6f4 v[66:69], v[2:9], v[196:203], v[66:69]
	s_add_u32 s22, s22, 0x80000
	s_addc_u32 s23, s23, 0
	v_mfma_f32_16x16x128_f8f6f4 v[54:57], v[10:17], v[204:211], v[54:57]
	v_mfma_f32_16x16x128_f8f6f4 v[50:53], v[2:9], v[204:211], v[50:53]
	s_mov_b32 m0, s39
	v_mfma_f32_16x16x128_f8f6f4 v[38:41], v[10:17], v[212:219], v[38:41]
	v_mfma_f32_16x16x128_f8f6f4 v[34:37], v[2:9], v[212:219], v[34:37]
	s_barrier
	ds_read_b128 v[2:5], v246
	ds_read_b128 v[6:9], v246 offset:1024
	ds_read_b128 v[10:13], v246 offset:2048
	ds_read_b128 v[14:17], v246 offset:3072
	ds_read_b128 v[18:21], v247
	ds_read_b128 v[22:25], v247 offset:1024
	ds_read_b128 v[26:29], v247 offset:2048
	ds_read_b128 v[30:33], v247 offset:3072
	ds_read_b128 v[188:191], v185 offset:32768
	ds_read_b128 v[192:195], v185 offset:33792
	ds_read_b128 v[196:199], v185 offset:34816
	ds_read_b128 v[200:203], v185 offset:35840
	ds_read_b128 v[204:207], v185 offset:36864
	ds_read_b128 v[208:211], v185 offset:37888
	ds_read_b128 v[212:215], v185 offset:38912
	ds_read_b128 v[216:219], v185 offset:39936
	global_load_lds_dwordx4 v162, s[22:23]
	s_mov_b32 m0, s40
	s_nop 0
	global_load_lds_dwordx4 v172, s[22:23]
	s_waitcnt vmcnt(8)
	s_waitcnt lgkmcnt(0)
	s_barrier
	v_mfma_f32_16x16x128_f8f6f4 v[158:161], v[2:9], v[188:195], v[158:161]
	v_mfma_f32_16x16x128_f8f6f4 v[154:157], v[10:17], v[188:195], v[154:157]
	v_mfma_f32_16x16x128_f8f6f4 v[146:149], v[2:9], v[196:203], v[146:149]
	v_mfma_f32_16x16x128_f8f6f4 v[138:141], v[10:17], v[196:203], v[138:141]
	v_mfma_f32_16x16x128_f8f6f4 v[130:133], v[2:9], v[204:211], v[130:133]
	v_mfma_f32_16x16x128_f8f6f4 v[122:125], v[10:17], v[204:211], v[122:125]
	v_mfma_f32_16x16x128_f8f6f4 v[114:117], v[2:9], v[212:219], v[114:117]
	v_mfma_f32_16x16x128_f8f6f4 v[106:109], v[10:17], v[212:219], v[106:109]
	v_mfma_f32_16x16x128_f8f6f4 v[150:153], v[18:25], v[188:195], v[150:153]
	v_mfma_f32_16x16x128_f8f6f4 v[142:145], v[26:33], v[188:195], v[142:145]
	v_mfma_f32_16x16x128_f8f6f4 v[134:137], v[18:25], v[196:203], v[134:137]
	v_mfma_f32_16x16x128_f8f6f4 v[126:129], v[26:33], v[196:203], v[126:129]
	s_add_i32 s22, s30, s37
	s_mov_b32 m0, s22
	v_mfma_f32_16x16x128_f8f6f4 v[118:121], v[18:25], v[204:211], v[118:121]
	v_mfma_f32_16x16x128_f8f6f4 v[110:113], v[26:33], v[204:211], v[110:113]
	s_add_u32 s0, s0, 0x80
	s_addc_u32 s1, s1, 0
	v_mfma_f32_16x16x128_f8f6f4 v[102:105], v[18:25], v[212:219], v[102:105]
	v_mfma_f32_16x16x128_f8f6f4 v[98:101], v[26:33], v[212:219], v[98:101]
	s_barrier
	ds_read_b128 v[188:191], v185 offset:49152
	ds_read_b128 v[192:195], v185 offset:50176
	ds_read_b128 v[196:199], v185 offset:51200
	ds_read_b128 v[200:203], v185 offset:52224
	ds_read_b128 v[204:207], v185 offset:53248
	ds_read_b128 v[208:211], v185 offset:54272
	ds_read_b128 v[212:215], v185 offset:55296
	ds_read_b128 v[216:219], v185 offset:56320
	global_load_lds_dwordx4 v168, s[0:1]
	s_add_i32 m0, s22, 0x2000
	s_add_i32 s22, s31, s37
	global_load_lds_dwordx4 v170, s[0:1]
	s_add_u32 s0, s0, 0x80000
	s_addc_u32 s1, s1, 0
	s_mov_b32 m0, s22
	s_nop 0
	global_load_lds_dwordx4 v168, s[0:1]
	s_add_i32 m0, s22, 0x2000
	s_nop 0
	global_load_lds_dwordx4 v170, s[0:1]
	s_mov_b32 m0, s44
	s_nop 0
	global_load_lds_dwordx4 v162, s[98:99]
	s_mov_b32 m0, s45
	s_nop 0
	global_load_lds_dwordx4 v172, s[98:99]
	s_waitcnt vmcnt(8)
	s_waitcnt lgkmcnt(0)
	s_barrier
	v_mfma_f32_16x16x128_f8f6f4 v[94:97], v[2:9], v[188:195], v[94:97]
	v_mfma_f32_16x16x128_f8f6f4 v[90:93], v[10:17], v[188:195], v[90:93]
	v_mfma_f32_16x16x128_f8f6f4 v[78:81], v[2:9], v[196:203], v[78:81]
	v_mfma_f32_16x16x128_f8f6f4 v[74:77], v[10:17], v[196:203], v[74:77]
	v_mfma_f32_16x16x128_f8f6f4 v[62:65], v[2:9], v[204:211], v[62:65]
	v_mfma_f32_16x16x128_f8f6f4 v[58:61], v[10:17], v[204:211], v[58:61]
	v_mfma_f32_16x16x128_f8f6f4 v[46:49], v[2:9], v[212:219], v[46:49]
	v_mfma_f32_16x16x128_f8f6f4 v[42:45], v[10:17], v[212:219], v[42:45]
	v_mfma_f32_16x16x128_f8f6f4 v[86:89], v[18:25], v[188:195], v[86:89]
	v_mfma_f32_16x16x128_f8f6f4 v[82:85], v[26:33], v[188:195], v[82:85]
	s_add_i32 s29, s29, 2
	s_add_u32 s20, s20, 0x100
	v_mfma_f32_16x16x128_f8f6f4 v[70:73], v[18:25], v[196:203], v[70:73]
	v_mfma_f32_16x16x128_f8f6f4 v[66:69], v[26:33], v[196:203], v[66:69]
	s_addc_u32 s21, s21, 0
	s_add_u32 s27, s27, 0x100
	v_mfma_f32_16x16x128_f8f6f4 v[54:57], v[18:25], v[204:211], v[54:57]
	v_mfma_f32_16x16x128_f8f6f4 v[50:53], v[26:33], v[204:211], v[50:53]
	s_addc_u32 s28, s28, 0
	s_cmp_gt_u32 s29, 29
	v_mfma_f32_16x16x128_f8f6f4 v[38:41], v[18:25], v[212:219], v[38:41]
	v_mfma_f32_16x16x128_f8f6f4 v[34:37], v[26:33], v[212:219], v[34:37]
	s_barrier
	s_cbranch_scc0 .LBB0_271
	s_and_b64 vcc, exec, s[8:9]
	s_cbranch_vccz .LBB0_274
	s_barrier

.LBB0_839:
	ds_read_b128 v[26:29], v183
	ds_read_b128 v[30:33], v183 offset:1024
	ds_read_b128 v[18:21], v183 offset:2048
	ds_read_b128 v[22:25], v183 offset:3072
	ds_read_b128 v[10:13], v184
	ds_read_b128 v[14:17], v184 offset:1024
	ds_read_b128 v[2:5], v184 offset:2048
	ds_read_b128 v[6:9], v184 offset:3072
	s_add_u32 s30, s28, 0xfffc0080
	s_addc_u32 s31, s29, -1
	s_cmp_eq_u32 s53, 12
	s_cselect_b32 s35, s21, s31
	s_cselect_b32 s34, s49, s30
	s_cselect_b32 s31, s19, s52
	s_cselect_b32 s30, s50, s51
	s_add_i32 m0, s27, 0xc000
	ds_read_b128 v[174:177], v185
	ds_read_b128 v[178:181], v185 offset:1024
	ds_read_b128 v[188:191], v185 offset:2048
	ds_read_b128 v[192:195], v185 offset:3072
	ds_read_b128 v[196:199], v185 offset:4096
	ds_read_b128 v[200:203], v185 offset:5120
	ds_read_b128 v[204:207], v185 offset:6144
	ds_read_b128 v[208:211], v185 offset:7168
	global_load_lds_dwordx4 v162, s[28:29]
	s_add_i32 m0, s27, 0xe000
	s_nop 0
	global_load_lds_dwordx4 v172, s[28:29]
	s_waitcnt vmcnt(8)
	s_waitcnt lgkmcnt(0)
	s_barrier
	v_mfma_f32_16x16x128_f8f6f4 v[158:161], v[26:33], v[174:181], v[158:161]
	v_mfma_f32_16x16x128_f8f6f4 v[154:157], v[18:25], v[174:181], v[154:157]
	v_mfma_f32_16x16x128_f8f6f4 v[142:145], v[26:33], v[188:195], v[142:145]
	v_mfma_f32_16x16x128_f8f6f4 v[138:141], v[18:25], v[188:195], v[138:141]
	v_mfma_f32_16x16x128_f8f6f4 v[126:129], v[26:33], v[196:203], v[126:129]
	v_mfma_f32_16x16x128_f8f6f4 v[122:125], v[18:25], v[196:203], v[122:125]
	v_mfma_f32_16x16x128_f8f6f4 v[110:113], v[26:33], v[204:211], v[110:113]
	v_mfma_f32_16x16x128_f8f6f4 v[106:109], v[18:25], v[204:211], v[106:109]
	v_mfma_f32_16x16x128_f8f6f4 v[150:153], v[10:17], v[174:181], v[150:153]
	v_mfma_f32_16x16x128_f8f6f4 v[146:149], v[2:9], v[174:181], v[146:149]
	v_mfma_f32_16x16x128_f8f6f4 v[134:137], v[10:17], v[188:195], v[134:137]
	v_mfma_f32_16x16x128_f8f6f4 v[130:133], v[2:9], v[188:195], v[130:133]
	v_mfma_f32_16x16x128_f8f6f4 v[118:121], v[10:17], v[196:203], v[118:121]
	v_mfma_f32_16x16x128_f8f6f4 v[114:117], v[2:9], v[196:203], v[114:117]
	s_add_i32 s54, s46, s36
	s_mov_b32 m0, s54
	v_mfma_f32_16x16x128_f8f6f4 v[102:105], v[10:17], v[204:211], v[102:105]
	v_mfma_f32_16x16x128_f8f6f4 v[98:101], v[2:9], v[204:211], v[98:101]
	s_barrier
	ds_read_b128 v[188:191], v185 offset:16384
	ds_read_b128 v[192:195], v185 offset:17408
	ds_read_b128 v[196:199], v185 offset:18432
	ds_read_b128 v[200:203], v185 offset:19456
	ds_read_b128 v[204:207], v185 offset:20480
	ds_read_b128 v[208:211], v185 offset:21504
	ds_read_b128 v[212:215], v185 offset:22528
	ds_read_b128 v[216:219], v185 offset:23552
	global_load_lds_dwordx4 v168, s[30:31]
	s_add_i32 m0, s54, 0x2000
	s_add_u32 s54, s30, 0x40000
	s_addc_u32 s55, s31, 0
	s_add_i32 s56, s47, s36
	global_load_lds_dwordx4 v170, s[30:31]
	s_mov_b32 m0, s56
	global_load_lds_dwordx4 v168, s[54:55]
	s_add_i32 m0, s56, 0x2000
	s_nop 0
	global_load_lds_dwordx4 v170, s[54:55]
	s_mov_b32 m0, s27
	s_nop 0
	global_load_lds_dwordx4 v162, s[34:35]
	s_mov_b32 m0, s37
	s_nop 0
	global_load_lds_dwordx4 v172, s[34:35]
	s_waitcnt vmcnt(8)
	s_waitcnt lgkmcnt(0)
	s_barrier
	v_mfma_f32_16x16x128_f8f6f4 v[94:97], v[26:33], v[188:195], v[94:97]
	v_mfma_f32_16x16x128_f8f6f4 v[90:93], v[18:25], v[188:195], v[90:93]
	v_mfma_f32_16x16x128_f8f6f4 v[78:81], v[26:33], v[196:203], v[78:81]
	v_mfma_f32_16x16x128_f8f6f4 v[74:77], v[18:25], v[196:203], v[74:77]
	v_mfma_f32_16x16x128_f8f6f4 v[62:65], v[26:33], v[204:211], v[62:65]
	v_mfma_f32_16x16x128_f8f6f4 v[58:61], v[18:25], v[204:211], v[58:61]
	v_mfma_f32_16x16x128_f8f6f4 v[46:49], v[26:33], v[212:219], v[46:49]
	v_mfma_f32_16x16x128_f8f6f4 v[42:45], v[18:25], v[212:219], v[42:45]
	s_add_i32 s54, 0, 0x18000
	s_add_i32 s55, 0, 0x1c000
	v_mfma_f32_16x16x128_f8f6f4 v[86:89], v[10:17], v[188:195], v[86:89]
	v_mfma_f32_16x16x128_f8f6f4 v[82:85], v[2:9], v[188:195], v[82:85]
	s_add_u32 s98, s34, 0x80
	s_addc_u32 s99, s35, 0
	v_mfma_f32_16x16x128_f8f6f4 v[70:73], v[10:17], v[196:203], v[70:73]
	v_mfma_f32_16x16x128_f8f6f4 v[66:69], v[2:9], v[196:203], v[66:69]
	s_add_u32 s34, s34, 0x40000
	s_addc_u32 s35, s35, 0
	v_mfma_f32_16x16x128_f8f6f4 v[54:57], v[10:17], v[204:211], v[54:57]
	v_mfma_f32_16x16x128_f8f6f4 v[50:53], v[2:9], v[204:211], v[50:53]
	s_mov_b32 m0, s38
	v_mfma_f32_16x16x128_f8f6f4 v[38:41], v[10:17], v[212:219], v[38:41]
	v_mfma_f32_16x16x128_f8f6f4 v[34:37], v[2:9], v[212:219], v[34:37]
	s_barrier
	ds_read_b128 v[2:5], v246
	ds_read_b128 v[6:9], v246 offset:1024
	ds_read_b128 v[10:13], v246 offset:2048
	ds_read_b128 v[14:17], v246 offset:3072
	ds_read_b128 v[18:21], v247
	ds_read_b128 v[22:25], v247 offset:1024
	ds_read_b128 v[26:29], v247 offset:2048
	ds_read_b128 v[30:33], v247 offset:3072
	ds_read_b128 v[188:191], v185 offset:32768
	ds_read_b128 v[192:195], v185 offset:33792
	ds_read_b128 v[196:199], v185 offset:34816
	ds_read_b128 v[200:203], v185 offset:35840
	ds_read_b128 v[204:207], v185 offset:36864
	ds_read_b128 v[208:211], v185 offset:37888
	ds_read_b128 v[212:215], v185 offset:38912
	ds_read_b128 v[216:219], v185 offset:39936
	global_load_lds_dwordx4 v162, s[34:35]
	s_mov_b32 m0, s39
	s_nop 0
	global_load_lds_dwordx4 v172, s[34:35]
	s_waitcnt vmcnt(8)
	s_waitcnt lgkmcnt(0)
	s_barrier
	v_mfma_f32_16x16x128_f8f6f4 v[158:161], v[2:9], v[188:195], v[158:161]
	v_mfma_f32_16x16x128_f8f6f4 v[154:157], v[10:17], v[188:195], v[154:157]
	v_mfma_f32_16x16x128_f8f6f4 v[142:145], v[2:9], v[196:203], v[142:145]
	v_mfma_f32_16x16x128_f8f6f4 v[138:141], v[10:17], v[196:203], v[138:141]
	v_mfma_f32_16x16x128_f8f6f4 v[126:129], v[2:9], v[204:211], v[126:129]
	v_mfma_f32_16x16x128_f8f6f4 v[122:125], v[10:17], v[204:211], v[122:125]
	v_mfma_f32_16x16x128_f8f6f4 v[110:113], v[2:9], v[212:219], v[110:113]
	v_mfma_f32_16x16x128_f8f6f4 v[106:109], v[10:17], v[212:219], v[106:109]
	v_mfma_f32_16x16x128_f8f6f4 v[150:153], v[18:25], v[188:195], v[150:153]
	v_mfma_f32_16x16x128_f8f6f4 v[146:149], v[26:33], v[188:195], v[146:149]
	v_mfma_f32_16x16x128_f8f6f4 v[134:137], v[18:25], v[196:203], v[134:137]
	v_mfma_f32_16x16x128_f8f6f4 v[130:133], v[26:33], v[196:203], v[130:133]
	s_add_i32 s34, s54, s36
	s_mov_b32 m0, s34
	v_mfma_f32_16x16x128_f8f6f4 v[118:121], v[18:25], v[204:211], v[118:121]
	v_mfma_f32_16x16x128_f8f6f4 v[114:117], v[26:33], v[204:211], v[114:117]
	s_add_u32 s30, s30, 0x80
	s_addc_u32 s31, s31, 0
	v_mfma_f32_16x16x128_f8f6f4 v[102:105], v[18:25], v[212:219], v[102:105]
	v_mfma_f32_16x16x128_f8f6f4 v[98:101], v[26:33], v[212:219], v[98:101]
	s_barrier
	ds_read_b128 v[188:191], v185 offset:49152
	ds_read_b128 v[192:195], v185 offset:50176
	ds_read_b128 v[196:199], v185 offset:51200
	ds_read_b128 v[200:203], v185 offset:52224
	ds_read_b128 v[204:207], v185 offset:53248
	ds_read_b128 v[208:211], v185 offset:54272
	ds_read_b128 v[212:215], v185 offset:55296
	ds_read_b128 v[216:219], v185 offset:56320
	global_load_lds_dwordx4 v168, s[30:31]
	s_add_i32 m0, s34, 0x2000
	s_add_i32 s34, s55, s36
	global_load_lds_dwordx4 v170, s[30:31]
	s_add_u32 s30, s30, 0x40000
	s_addc_u32 s31, s31, 0
	s_mov_b32 m0, s34
	s_nop 0
	global_load_lds_dwordx4 v168, s[30:31]
	s_add_i32 m0, s34, 0x2000
	s_nop 0
	global_load_lds_dwordx4 v170, s[30:31]
	s_mov_b32 m0, s43
	s_nop 0
	global_load_lds_dwordx4 v162, s[98:99]
	s_mov_b32 m0, s44
	s_nop 0
	global_load_lds_dwordx4 v172, s[98:99]
	s_waitcnt vmcnt(8)
	s_waitcnt lgkmcnt(0)
	s_barrier
	v_mfma_f32_16x16x128_f8f6f4 v[94:97], v[2:9], v[188:195], v[94:97]
	v_mfma_f32_16x16x128_f8f6f4 v[90:93], v[10:17], v[188:195], v[90:93]
	v_mfma_f32_16x16x128_f8f6f4 v[78:81], v[2:9], v[196:203], v[78:81]
	v_mfma_f32_16x16x128_f8f6f4 v[74:77], v[10:17], v[196:203], v[74:77]
	v_mfma_f32_16x16x128_f8f6f4 v[62:65], v[2:9], v[204:211], v[62:65]
	v_mfma_f32_16x16x128_f8f6f4 v[58:61], v[10:17], v[204:211], v[58:61]
	v_mfma_f32_16x16x128_f8f6f4 v[46:49], v[2:9], v[212:219], v[46:49]
	v_mfma_f32_16x16x128_f8f6f4 v[42:45], v[10:17], v[212:219], v[42:45]
	v_mfma_f32_16x16x128_f8f6f4 v[86:89], v[18:25], v[188:195], v[86:89]
	v_mfma_f32_16x16x128_f8f6f4 v[82:85], v[26:33], v[188:195], v[82:85]
	s_add_i32 s53, s53, 2
	s_add_u32 s28, s28, 0x100
	v_mfma_f32_16x16x128_f8f6f4 v[70:73], v[18:25], v[196:203], v[70:73]
	v_mfma_f32_16x16x128_f8f6f4 v[66:69], v[26:33], v[196:203], v[66:69]
	s_addc_u32 s29, s29, 0
	s_add_u32 s51, s51, 0x100
	v_mfma_f32_16x16x128_f8f6f4 v[54:57], v[18:25], v[204:211], v[54:57]
	v_mfma_f32_16x16x128_f8f6f4 v[50:53], v[26:33], v[204:211], v[50:53]
	s_addc_u32 s52, s52, 0
	s_cmp_gt_u32 s53, 13
	v_mfma_f32_16x16x128_f8f6f4 v[38:41], v[18:25], v[212:219], v[38:41]
	v_mfma_f32_16x16x128_f8f6f4 v[34:37], v[26:33], v[212:219], v[34:37]
	s_barrier
	s_cbranch_scc0 .LBB0_839
	s_and_b64 vcc, exec, s[10:11]
	s_cbranch_vccz .LBB0_842
	s_barrier

.LBB0_863:
	ds_read_b128 v[146:149], v154
	ds_read_b128 v[158:161], v154 offset:1024
	ds_read_b128 v[162:165], v154 offset:2048
	ds_read_b128 v[166:169], v154 offset:3072
	ds_read_b128 v[170:173], v155
	ds_read_b128 v[174:177], v155 offset:1024
	ds_read_b128 v[178:181], v155 offset:2048
	ds_read_b128 v[182:185], v155 offset:3072
	s_add_u32 s22, s20, 0xfff80080
	s_addc_u32 s23, s21, -1
	s_cmp_eq_u32 s43, 28
	s_cselect_b32 s25, s13, s23
	s_cselect_b32 s24, s39, s22
	s_cselect_b32 s23, s11, s42
	s_cselect_b32 s22, s40, s41
	s_add_i32 m0, s19, 0xc000
	ds_read_b128 v[186:189], v156
	ds_read_b128 v[190:193], v156 offset:1024
	ds_read_b128 v[194:197], v156 offset:2048
	ds_read_b128 v[198:201], v156 offset:3072
	ds_read_b128 v[202:205], v156 offset:4096
	ds_read_b128 v[206:209], v156 offset:5120
	ds_read_b128 v[210:213], v156 offset:6144
	ds_read_b128 v[214:217], v156 offset:7168
	global_load_lds_dwordx4 v138, s[20:21]
	s_add_i32 m0, s19, 0xe000
	s_nop 0
	global_load_lds_dwordx4 v140, s[20:21]
	s_waitcnt vmcnt(8)
	s_waitcnt lgkmcnt(0)
	s_barrier
	v_mfma_f32_16x16x32_bf16 v[126:129], v[146:149], v[186:189], v[126:129]
	v_mfma_f32_16x16x32_bf16 v[126:129], v[158:161], v[190:193], v[126:129]
	v_mfma_f32_16x16x32_bf16 v[122:125], v[162:165], v[186:189], v[122:125]
	v_mfma_f32_16x16x32_bf16 v[122:125], v[166:169], v[190:193], v[122:125]
	v_mfma_f32_16x16x32_bf16 v[110:113], v[146:149], v[194:197], v[110:113]
	v_mfma_f32_16x16x32_bf16 v[110:113], v[158:161], v[198:201], v[110:113]
	v_mfma_f32_16x16x32_bf16 v[106:109], v[162:165], v[194:197], v[106:109]
	v_mfma_f32_16x16x32_bf16 v[106:109], v[166:169], v[198:201], v[106:109]
	v_mfma_f32_16x16x32_bf16 v[94:97], v[146:149], v[202:205], v[94:97]
	v_mfma_f32_16x16x32_bf16 v[94:97], v[158:161], v[206:209], v[94:97]
	v_mfma_f32_16x16x32_bf16 v[90:93], v[162:165], v[202:205], v[90:93]
	v_mfma_f32_16x16x32_bf16 v[90:93], v[166:169], v[206:209], v[90:93]
	v_mfma_f32_16x16x32_bf16 v[78:81], v[146:149], v[210:213], v[78:81]
	v_mfma_f32_16x16x32_bf16 v[78:81], v[158:161], v[214:217], v[78:81]
	v_mfma_f32_16x16x32_bf16 v[74:77], v[162:165], v[210:213], v[74:77]
	v_mfma_f32_16x16x32_bf16 v[74:77], v[166:169], v[214:217], v[74:77]
	v_mfma_f32_16x16x32_bf16 v[118:121], v[170:173], v[186:189], v[118:121]
	v_mfma_f32_16x16x32_bf16 v[118:121], v[174:177], v[190:193], v[118:121]
	v_mfma_f32_16x16x32_bf16 v[114:117], v[178:181], v[186:189], v[114:117]
	v_mfma_f32_16x16x32_bf16 v[114:117], v[182:185], v[190:193], v[114:117]
	v_mfma_f32_16x16x32_bf16 v[102:105], v[170:173], v[194:197], v[102:105]
	v_mfma_f32_16x16x32_bf16 v[102:105], v[174:177], v[198:201], v[102:105]
	v_mfma_f32_16x16x32_bf16 v[98:101], v[178:181], v[194:197], v[98:101]
	v_mfma_f32_16x16x32_bf16 v[98:101], v[182:185], v[198:201], v[98:101]
	v_mfma_f32_16x16x32_bf16 v[86:89], v[170:173], v[202:205], v[86:89]
	v_mfma_f32_16x16x32_bf16 v[86:89], v[174:177], v[206:209], v[86:89]
	v_mfma_f32_16x16x32_bf16 v[82:85], v[178:181], v[202:205], v[82:85]
	v_mfma_f32_16x16x32_bf16 v[82:85], v[182:185], v[206:209], v[82:85]
	v_mfma_f32_16x16x32_bf16 v[70:73], v[170:173], v[210:213], v[70:73]
	v_mfma_f32_16x16x32_bf16 v[70:73], v[174:177], v[214:217], v[70:73]
	s_add_i32 s44, s36, s27
	s_mov_b32 m0, s44
	v_mfma_f32_16x16x32_bf16 v[66:69], v[178:181], v[210:213], v[66:69]
	v_mfma_f32_16x16x32_bf16 v[66:69], v[182:185], v[214:217], v[66:69]
	s_barrier
	ds_read_b128 v[186:189], v156 offset:16384
	ds_read_b128 v[190:193], v156 offset:17408
	ds_read_b128 v[194:197], v156 offset:18432
	ds_read_b128 v[198:201], v156 offset:19456
	ds_read_b128 v[202:205], v156 offset:20480
	ds_read_b128 v[206:209], v156 offset:21504
	ds_read_b128 v[210:213], v156 offset:22528
	ds_read_b128 v[214:217], v156 offset:23552
	global_load_lds_dwordx4 v132, s[22:23]
	s_add_i32 m0, s44, 0x2000
	s_add_u32 s44, s22, 0x80000
	s_addc_u32 s45, s23, 0
	s_add_i32 s46, s37, s27
	global_load_lds_dwordx4 v136, s[22:23]
	s_mov_b32 m0, s46
	global_load_lds_dwordx4 v132, s[44:45]
	s_add_i32 m0, s46, 0x2000
	s_nop 0
	global_load_lds_dwordx4 v136, s[44:45]
	s_mov_b32 m0, s19
	s_nop 0
	global_load_lds_dwordx4 v130, s[24:25]
	s_mov_b32 m0, s28
	s_nop 0
	global_load_lds_dwordx4 v134, s[24:25]
	s_waitcnt vmcnt(8)
	s_waitcnt lgkmcnt(0)
	s_barrier
	v_mfma_f32_16x16x32_bf16 v[62:65], v[146:149], v[186:189], v[62:65]
	v_mfma_f32_16x16x32_bf16 v[62:65], v[158:161], v[190:193], v[62:65]
	v_mfma_f32_16x16x32_bf16 v[58:61], v[162:165], v[186:189], v[58:61]
	v_mfma_f32_16x16x32_bf16 v[58:61], v[166:169], v[190:193], v[58:61]
	v_mfma_f32_16x16x32_bf16 v[46:49], v[146:149], v[194:197], v[46:49]
	v_mfma_f32_16x16x32_bf16 v[46:49], v[158:161], v[198:201], v[46:49]
	v_mfma_f32_16x16x32_bf16 v[42:45], v[162:165], v[194:197], v[42:45]
	v_mfma_f32_16x16x32_bf16 v[42:45], v[166:169], v[198:201], v[42:45]
	v_mfma_f32_16x16x32_bf16 v[30:33], v[146:149], v[202:205], v[30:33]
	v_mfma_f32_16x16x32_bf16 v[30:33], v[158:161], v[206:209], v[30:33]
	v_mfma_f32_16x16x32_bf16 v[26:29], v[162:165], v[202:205], v[26:29]
	v_mfma_f32_16x16x32_bf16 v[26:29], v[166:169], v[206:209], v[26:29]
	v_mfma_f32_16x16x32_bf16 v[14:17], v[146:149], v[210:213], v[14:17]
	v_mfma_f32_16x16x32_bf16 v[14:17], v[158:161], v[214:217], v[14:17]
	v_mfma_f32_16x16x32_bf16 v[10:13], v[162:165], v[210:213], v[10:13]
	v_mfma_f32_16x16x32_bf16 v[10:13], v[166:169], v[214:217], v[10:13]
	v_mfma_f32_16x16x32_bf16 v[54:57], v[170:173], v[186:189], v[54:57]
	v_mfma_f32_16x16x32_bf16 v[54:57], v[174:177], v[190:193], v[54:57]
	v_mfma_f32_16x16x32_bf16 v[50:53], v[178:181], v[186:189], v[50:53]
	v_mfma_f32_16x16x32_bf16 v[50:53], v[182:185], v[190:193], v[50:53]
	v_mfma_f32_16x16x32_bf16 v[38:41], v[170:173], v[194:197], v[38:41]
	v_mfma_f32_16x16x32_bf16 v[38:41], v[174:177], v[198:201], v[38:41]
	v_mfma_f32_16x16x32_bf16 v[34:37], v[178:181], v[194:197], v[34:37]
	v_mfma_f32_16x16x32_bf16 v[34:37], v[182:185], v[198:201], v[34:37]
	s_add_i32 s44, 0, 0x18000
	s_add_i32 s45, 0, 0x1c000
	v_mfma_f32_16x16x32_bf16 v[22:25], v[170:173], v[202:205], v[22:25]
	v_mfma_f32_16x16x32_bf16 v[22:25], v[174:177], v[206:209], v[22:25]
	s_add_u32 s98, s24, 0x80
	s_addc_u32 s99, s25, 0
	v_mfma_f32_16x16x32_bf16 v[18:21], v[178:181], v[202:205], v[18:21]
	v_mfma_f32_16x16x32_bf16 v[18:21], v[182:185], v[206:209], v[18:21]
	s_add_u32 s24, s24, 0x80000
	s_addc_u32 s25, s25, 0
	v_mfma_f32_16x16x32_bf16 v[6:9], v[170:173], v[210:213], v[6:9]
	v_mfma_f32_16x16x32_bf16 v[6:9], v[174:177], v[214:217], v[6:9]
	s_mov_b32 m0, s29
	v_mfma_f32_16x16x32_bf16 v[2:5], v[178:181], v[210:213], v[2:5]
	v_mfma_f32_16x16x32_bf16 v[2:5], v[182:185], v[214:217], v[2:5]
	s_barrier
	ds_read_b128 v[146:149], v246
	ds_read_b128 v[158:161], v246 offset:1024
	ds_read_b128 v[162:165], v246 offset:2048
	ds_read_b128 v[166:169], v246 offset:3072
	ds_read_b128 v[170:173], v247
	ds_read_b128 v[174:177], v247 offset:1024
	ds_read_b128 v[178:181], v247 offset:2048
	ds_read_b128 v[182:185], v247 offset:3072
	ds_read_b128 v[186:189], v156 offset:32768
	ds_read_b128 v[190:193], v156 offset:33792
	ds_read_b128 v[194:197], v156 offset:34816
	ds_read_b128 v[198:201], v156 offset:35840
	ds_read_b128 v[202:205], v156 offset:36864
	ds_read_b128 v[206:209], v156 offset:37888
	ds_read_b128 v[210:213], v156 offset:38912
	ds_read_b128 v[214:217], v156 offset:39936
	global_load_lds_dwordx4 v130, s[24:25]
	s_mov_b32 m0, s30
	s_nop 0
	global_load_lds_dwordx4 v134, s[24:25]
	s_waitcnt vmcnt(8)
	s_waitcnt lgkmcnt(0)
	s_barrier
	v_mfma_f32_16x16x32_bf16 v[126:129], v[146:149], v[186:189], v[126:129]
	v_mfma_f32_16x16x32_bf16 v[126:129], v[158:161], v[190:193], v[126:129]
	v_mfma_f32_16x16x32_bf16 v[122:125], v[162:165], v[186:189], v[122:125]
	v_mfma_f32_16x16x32_bf16 v[122:125], v[166:169], v[190:193], v[122:125]
	v_mfma_f32_16x16x32_bf16 v[110:113], v[146:149], v[194:197], v[110:113]
	v_mfma_f32_16x16x32_bf16 v[110:113], v[158:161], v[198:201], v[110:113]
	v_mfma_f32_16x16x32_bf16 v[106:109], v[162:165], v[194:197], v[106:109]
	v_mfma_f32_16x16x32_bf16 v[106:109], v[166:169], v[198:201], v[106:109]
	v_mfma_f32_16x16x32_bf16 v[94:97], v[146:149], v[202:205], v[94:97]
	v_mfma_f32_16x16x32_bf16 v[94:97], v[158:161], v[206:209], v[94:97]
	v_mfma_f32_16x16x32_bf16 v[90:93], v[162:165], v[202:205], v[90:93]
	v_mfma_f32_16x16x32_bf16 v[90:93], v[166:169], v[206:209], v[90:93]
	v_mfma_f32_16x16x32_bf16 v[78:81], v[146:149], v[210:213], v[78:81]
	v_mfma_f32_16x16x32_bf16 v[78:81], v[158:161], v[214:217], v[78:81]
	v_mfma_f32_16x16x32_bf16 v[74:77], v[162:165], v[210:213], v[74:77]
	v_mfma_f32_16x16x32_bf16 v[74:77], v[166:169], v[214:217], v[74:77]
	v_mfma_f32_16x16x32_bf16 v[118:121], v[170:173], v[186:189], v[118:121]
	v_mfma_f32_16x16x32_bf16 v[118:121], v[174:177], v[190:193], v[118:121]
	v_mfma_f32_16x16x32_bf16 v[114:117], v[178:181], v[186:189], v[114:117]
	v_mfma_f32_16x16x32_bf16 v[114:117], v[182:185], v[190:193], v[114:117]
	v_mfma_f32_16x16x32_bf16 v[102:105], v[170:173], v[194:197], v[102:105]
	v_mfma_f32_16x16x32_bf16 v[102:105], v[174:177], v[198:201], v[102:105]
	v_mfma_f32_16x16x32_bf16 v[98:101], v[178:181], v[194:197], v[98:101]
	v_mfma_f32_16x16x32_bf16 v[98:101], v[182:185], v[198:201], v[98:101]
	v_mfma_f32_16x16x32_bf16 v[86:89], v[170:173], v[202:205], v[86:89]
	v_mfma_f32_16x16x32_bf16 v[86:89], v[174:177], v[206:209], v[86:89]
	v_mfma_f32_16x16x32_bf16 v[82:85], v[178:181], v[202:205], v[82:85]
	v_mfma_f32_16x16x32_bf16 v[82:85], v[182:185], v[206:209], v[82:85]
	s_add_i32 s24, s44, s27
	s_mov_b32 m0, s24
	v_mfma_f32_16x16x32_bf16 v[70:73], v[170:173], v[210:213], v[70:73]
	v_mfma_f32_16x16x32_bf16 v[70:73], v[174:177], v[214:217], v[70:73]
	s_add_u32 s22, s22, 0x80
	s_addc_u32 s23, s23, 0
	v_mfma_f32_16x16x32_bf16 v[66:69], v[178:181], v[210:213], v[66:69]
	v_mfma_f32_16x16x32_bf16 v[66:69], v[182:185], v[214:217], v[66:69]
	s_barrier
	ds_read_b128 v[186:189], v156 offset:49152
	ds_read_b128 v[190:193], v156 offset:50176
	ds_read_b128 v[194:197], v156 offset:51200
	ds_read_b128 v[198:201], v156 offset:52224
	ds_read_b128 v[202:205], v156 offset:53248
	ds_read_b128 v[206:209], v156 offset:54272
	ds_read_b128 v[210:213], v156 offset:55296
	ds_read_b128 v[214:217], v156 offset:56320
	global_load_lds_dwordx4 v132, s[22:23]
	s_add_i32 m0, s24, 0x2000
	s_add_i32 s24, s45, s27
	global_load_lds_dwordx4 v136, s[22:23]
	s_add_u32 s22, s22, 0x80000
	s_addc_u32 s23, s23, 0
	s_mov_b32 m0, s24
	s_nop 0
	global_load_lds_dwordx4 v132, s[22:23]
	s_add_i32 m0, s24, 0x2000
	s_nop 0
	global_load_lds_dwordx4 v136, s[22:23]
	s_mov_b32 m0, s33
	s_nop 0
	global_load_lds_dwordx4 v130, s[98:99]
	s_mov_b32 m0, s34
	s_nop 0
	global_load_lds_dwordx4 v134, s[98:99]
	s_waitcnt vmcnt(8)
	s_waitcnt lgkmcnt(0)
	s_barrier
	v_mfma_f32_16x16x32_bf16 v[62:65], v[146:149], v[186:189], v[62:65]
	v_mfma_f32_16x16x32_bf16 v[62:65], v[158:161], v[190:193], v[62:65]
	v_mfma_f32_16x16x32_bf16 v[58:61], v[162:165], v[186:189], v[58:61]
	v_mfma_f32_16x16x32_bf16 v[58:61], v[166:169], v[190:193], v[58:61]
	v_mfma_f32_16x16x32_bf16 v[46:49], v[146:149], v[194:197], v[46:49]
	v_mfma_f32_16x16x32_bf16 v[46:49], v[158:161], v[198:201], v[46:49]
	v_mfma_f32_16x16x32_bf16 v[42:45], v[162:165], v[194:197], v[42:45]
	v_mfma_f32_16x16x32_bf16 v[42:45], v[166:169], v[198:201], v[42:45]
	v_mfma_f32_16x16x32_bf16 v[30:33], v[146:149], v[202:205], v[30:33]
	v_mfma_f32_16x16x32_bf16 v[30:33], v[158:161], v[206:209], v[30:33]
	v_mfma_f32_16x16x32_bf16 v[26:29], v[162:165], v[202:205], v[26:29]
	v_mfma_f32_16x16x32_bf16 v[26:29], v[166:169], v[206:209], v[26:29]
	v_mfma_f32_16x16x32_bf16 v[14:17], v[146:149], v[210:213], v[14:17]
	v_mfma_f32_16x16x32_bf16 v[14:17], v[158:161], v[214:217], v[14:17]
	v_mfma_f32_16x16x32_bf16 v[10:13], v[162:165], v[210:213], v[10:13]
	v_mfma_f32_16x16x32_bf16 v[10:13], v[166:169], v[214:217], v[10:13]
	v_mfma_f32_16x16x32_bf16 v[54:57], v[170:173], v[186:189], v[54:57]
	v_mfma_f32_16x16x32_bf16 v[54:57], v[174:177], v[190:193], v[54:57]
	v_mfma_f32_16x16x32_bf16 v[50:53], v[178:181], v[186:189], v[50:53]
	v_mfma_f32_16x16x32_bf16 v[50:53], v[182:185], v[190:193], v[50:53]
	v_mfma_f32_16x16x32_bf16 v[38:41], v[170:173], v[194:197], v[38:41]
	v_mfma_f32_16x16x32_bf16 v[38:41], v[174:177], v[198:201], v[38:41]
	v_mfma_f32_16x16x32_bf16 v[34:37], v[178:181], v[194:197], v[34:37]
	v_mfma_f32_16x16x32_bf16 v[34:37], v[182:185], v[198:201], v[34:37]
	v_mfma_f32_16x16x32_bf16 v[22:25], v[170:173], v[202:205], v[22:25]
	v_mfma_f32_16x16x32_bf16 v[22:25], v[174:177], v[206:209], v[22:25]
	s_add_i32 s43, s43, 2
	s_add_u32 s20, s20, 0x100
	v_mfma_f32_16x16x32_bf16 v[18:21], v[178:181], v[202:205], v[18:21]
	v_mfma_f32_16x16x32_bf16 v[18:21], v[182:185], v[206:209], v[18:21]
	s_addc_u32 s21, s21, 0
	s_add_u32 s41, s41, 0x100
	v_mfma_f32_16x16x32_bf16 v[6:9], v[170:173], v[210:213], v[6:9]
	v_mfma_f32_16x16x32_bf16 v[6:9], v[174:177], v[214:217], v[6:9]
	s_addc_u32 s42, s42, 0
	s_cmp_gt_u32 s43, 29
	v_mfma_f32_16x16x32_bf16 v[2:5], v[178:181], v[210:213], v[2:5]
	v_mfma_f32_16x16x32_bf16 v[2:5], v[182:185], v[214:217], v[2:5]
	s_barrier
	s_cbranch_scc0 .LBB0_863
	s_and_b64 vcc, exec, s[8:9]
	s_cbranch_vccz .LBB0_866
	s_barrier

.LBB0_941:
	ds_read_b128 v[90:93], v188
	ds_read_b128 v[94:97], v188 offset:1024
	ds_read_b128 v[102:105], v188 offset:2048
	ds_read_b128 v[110:113], v188 offset:3072
	ds_read_b128 v[146:149], v189
	ds_read_b128 v[150:153], v189 offset:1024
	ds_read_b128 v[154:157], v189 offset:2048
	ds_read_b128 v[158:161], v189 offset:3072
	s_add_u32 s30, s28, 0xfff00080
	s_addc_u32 s31, s29, -1
	s_cmp_eq_u32 s51, 60
	s_cselect_b32 s35, s21, s31
	s_cselect_b32 s34, s27, s30
	s_cselect_b32 s31, s19, s50
	s_cselect_b32 s30, s48, s49
	s_add_i32 m0, s36, 0xc000
	ds_read_b128 v[178:181], v190
	ds_read_b128 v[182:185], v190 offset:1024
	ds_read_b128 v[192:195], v190 offset:2048
	ds_read_b128 v[196:199], v190 offset:3072
	ds_read_b128 v[200:203], v190 offset:4096
	ds_read_b128 v[204:207], v190 offset:5120
	ds_read_b128 v[208:211], v190 offset:6144
	ds_read_b128 v[212:215], v190 offset:7168
	global_load_lds_dwordx4 v170, s[28:29]
	s_add_i32 m0, s36, 0xe000
	s_nop 0
	global_load_lds_dwordx4 v172, s[28:29]
	s_waitcnt vmcnt(8)
	s_waitcnt lgkmcnt(0)
	s_barrier
	v_mfma_f32_16x16x32_bf16 v[142:145], v[90:93], v[178:181], v[142:145]
	v_mfma_f32_16x16x32_bf16 v[142:145], v[94:97], v[182:185], v[142:145]
	v_mfma_f32_16x16x32_bf16 v[138:141], v[102:105], v[178:181], v[138:141]
	v_mfma_f32_16x16x32_bf16 v[138:141], v[110:113], v[182:185], v[138:141]
	v_mfma_f32_16x16x32_bf16 v[126:129], v[90:93], v[192:195], v[126:129]
	v_mfma_f32_16x16x32_bf16 v[126:129], v[94:97], v[196:199], v[126:129]
	v_mfma_f32_16x16x32_bf16 v[122:125], v[102:105], v[192:195], v[122:125]
	v_mfma_f32_16x16x32_bf16 v[122:125], v[110:113], v[196:199], v[122:125]
	v_mfma_f32_16x16x32_bf16 v[106:109], v[90:93], v[200:203], v[106:109]
	v_mfma_f32_16x16x32_bf16 v[106:109], v[94:97], v[204:207], v[106:109]
	v_mfma_f32_16x16x32_bf16 v[98:101], v[102:105], v[200:203], v[98:101]
	v_mfma_f32_16x16x32_bf16 v[98:101], v[110:113], v[204:207], v[98:101]
	v_mfma_f32_16x16x32_bf16 v[78:81], v[90:93], v[208:211], v[78:81]
	v_mfma_f32_16x16x32_bf16 v[78:81], v[94:97], v[212:215], v[78:81]
	v_mfma_f32_16x16x32_bf16 v[74:77], v[102:105], v[208:211], v[74:77]
	v_mfma_f32_16x16x32_bf16 v[74:77], v[110:113], v[212:215], v[74:77]
	v_mfma_f32_16x16x32_bf16 v[134:137], v[146:149], v[178:181], v[134:137]
	v_mfma_f32_16x16x32_bf16 v[134:137], v[150:153], v[182:185], v[134:137]
	v_mfma_f32_16x16x32_bf16 v[130:133], v[154:157], v[178:181], v[130:133]
	v_mfma_f32_16x16x32_bf16 v[130:133], v[158:161], v[182:185], v[130:133]
	v_mfma_f32_16x16x32_bf16 v[118:121], v[146:149], v[192:195], v[118:121]
	v_mfma_f32_16x16x32_bf16 v[118:121], v[150:153], v[196:199], v[118:121]
	v_mfma_f32_16x16x32_bf16 v[114:117], v[154:157], v[192:195], v[114:117]
	v_mfma_f32_16x16x32_bf16 v[114:117], v[158:161], v[196:199], v[114:117]
	v_mfma_f32_16x16x32_bf16 v[86:89], v[146:149], v[200:203], v[86:89]
	v_mfma_f32_16x16x32_bf16 v[86:89], v[150:153], v[204:207], v[86:89]
	v_mfma_f32_16x16x32_bf16 v[82:85], v[154:157], v[200:203], v[82:85]
	v_mfma_f32_16x16x32_bf16 v[82:85], v[158:161], v[204:207], v[82:85]
	v_mfma_f32_16x16x32_bf16 v[70:73], v[146:149], v[208:211], v[70:73]
	v_mfma_f32_16x16x32_bf16 v[70:73], v[150:153], v[212:215], v[70:73]
	s_add_i32 s52, s45, s33
	s_mov_b32 m0, s52
	v_mfma_f32_16x16x32_bf16 v[66:69], v[154:157], v[208:211], v[66:69]
	v_mfma_f32_16x16x32_bf16 v[66:69], v[158:161], v[212:215], v[66:69]
	s_barrier
	ds_read_b128 v[178:181], v190 offset:16384
	ds_read_b128 v[182:185], v190 offset:17408
	ds_read_b128 v[192:195], v190 offset:18432
	ds_read_b128 v[196:199], v190 offset:19456
	ds_read_b128 v[200:203], v190 offset:20480
	ds_read_b128 v[204:207], v190 offset:21504
	ds_read_b128 v[208:211], v190 offset:22528
	ds_read_b128 v[212:215], v190 offset:23552
	global_load_lds_dwordx4 v164, s[30:31]
	s_add_i32 m0, s52, 0x2000
	s_add_u32 s52, s30, 0x100000
	s_addc_u32 s53, s31, 0
	s_add_i32 s54, s46, s33
	global_load_lds_dwordx4 v168, s[30:31]
	s_mov_b32 m0, s54
	global_load_lds_dwordx4 v164, s[52:53]
	s_add_i32 m0, s54, 0x2000
	s_nop 0
	global_load_lds_dwordx4 v168, s[52:53]
	s_mov_b32 m0, s36
	s_nop 0
	global_load_lds_dwordx4 v162, s[34:35]
	s_mov_b32 m0, s37
	s_nop 0
	global_load_lds_dwordx4 v166, s[34:35]
	s_waitcnt vmcnt(8)
	s_waitcnt lgkmcnt(0)
	s_barrier
	v_mfma_f32_16x16x32_bf16 v[62:65], v[90:93], v[178:181], v[62:65]
	v_mfma_f32_16x16x32_bf16 v[62:65], v[94:97], v[182:185], v[62:65]
	v_mfma_f32_16x16x32_bf16 v[58:61], v[102:105], v[178:181], v[58:61]
	v_mfma_f32_16x16x32_bf16 v[58:61], v[110:113], v[182:185], v[58:61]
	v_mfma_f32_16x16x32_bf16 v[46:49], v[90:93], v[192:195], v[46:49]
	v_mfma_f32_16x16x32_bf16 v[46:49], v[94:97], v[196:199], v[46:49]
	v_mfma_f32_16x16x32_bf16 v[42:45], v[102:105], v[192:195], v[42:45]
	v_mfma_f32_16x16x32_bf16 v[42:45], v[110:113], v[196:199], v[42:45]
	v_mfma_f32_16x16x32_bf16 v[30:33], v[90:93], v[200:203], v[30:33]
	v_mfma_f32_16x16x32_bf16 v[30:33], v[94:97], v[204:207], v[30:33]
	v_mfma_f32_16x16x32_bf16 v[26:29], v[102:105], v[200:203], v[26:29]
	v_mfma_f32_16x16x32_bf16 v[26:29], v[110:113], v[204:207], v[26:29]
	v_mfma_f32_16x16x32_bf16 v[14:17], v[90:93], v[208:211], v[14:17]
	v_mfma_f32_16x16x32_bf16 v[14:17], v[94:97], v[212:215], v[14:17]
	v_mfma_f32_16x16x32_bf16 v[10:13], v[102:105], v[208:211], v[10:13]
	v_mfma_f32_16x16x32_bf16 v[10:13], v[110:113], v[212:215], v[10:13]
	v_mfma_f32_16x16x32_bf16 v[54:57], v[146:149], v[178:181], v[54:57]
	v_mfma_f32_16x16x32_bf16 v[54:57], v[150:153], v[182:185], v[54:57]
	v_mfma_f32_16x16x32_bf16 v[50:53], v[154:157], v[178:181], v[50:53]
	v_mfma_f32_16x16x32_bf16 v[50:53], v[158:161], v[182:185], v[50:53]
	v_mfma_f32_16x16x32_bf16 v[38:41], v[146:149], v[192:195], v[38:41]
	v_mfma_f32_16x16x32_bf16 v[38:41], v[150:153], v[196:199], v[38:41]
	v_mfma_f32_16x16x32_bf16 v[34:37], v[154:157], v[192:195], v[34:37]
	v_mfma_f32_16x16x32_bf16 v[34:37], v[158:161], v[196:199], v[34:37]
	s_add_i32 s52, 0, 0x18000
	s_add_i32 s53, 0, 0x1c000
	v_mfma_f32_16x16x32_bf16 v[22:25], v[146:149], v[200:203], v[22:25]
	v_mfma_f32_16x16x32_bf16 v[22:25], v[150:153], v[204:207], v[22:25]
	s_add_u32 s98, s34, 0x80
	s_addc_u32 s99, s35, 0
	v_mfma_f32_16x16x32_bf16 v[18:21], v[154:157], v[200:203], v[18:21]
	v_mfma_f32_16x16x32_bf16 v[18:21], v[158:161], v[204:207], v[18:21]
	s_add_u32 s34, s34, 0x100000
	s_addc_u32 s35, s35, 0
	v_mfma_f32_16x16x32_bf16 v[6:9], v[146:149], v[208:211], v[6:9]
	v_mfma_f32_16x16x32_bf16 v[6:9], v[150:153], v[212:215], v[6:9]
	s_mov_b32 m0, s38
	v_mfma_f32_16x16x32_bf16 v[2:5], v[154:157], v[208:211], v[2:5]
	v_mfma_f32_16x16x32_bf16 v[2:5], v[158:161], v[212:215], v[2:5]
	s_barrier
	ds_read_b128 v[90:93], v246
	ds_read_b128 v[94:97], v246 offset:1024
	ds_read_b128 v[102:105], v246 offset:2048
	ds_read_b128 v[110:113], v246 offset:3072
	ds_read_b128 v[146:149], v247
	ds_read_b128 v[150:153], v247 offset:1024
	ds_read_b128 v[154:157], v247 offset:2048
	ds_read_b128 v[158:161], v247 offset:3072
	ds_read_b128 v[178:181], v190 offset:32768
	ds_read_b128 v[182:185], v190 offset:33792
	ds_read_b128 v[192:195], v190 offset:34816
	ds_read_b128 v[196:199], v190 offset:35840
	ds_read_b128 v[200:203], v190 offset:36864
	ds_read_b128 v[204:207], v190 offset:37888
	ds_read_b128 v[208:211], v190 offset:38912
	ds_read_b128 v[212:215], v190 offset:39936
	global_load_lds_dwordx4 v162, s[34:35]
	s_mov_b32 m0, s39
	s_nop 0
	global_load_lds_dwordx4 v166, s[34:35]
	s_waitcnt vmcnt(8)
	s_waitcnt lgkmcnt(0)
	s_barrier
	v_mfma_f32_16x16x32_bf16 v[142:145], v[90:93], v[178:181], v[142:145]
	v_mfma_f32_16x16x32_bf16 v[142:145], v[94:97], v[182:185], v[142:145]
	v_mfma_f32_16x16x32_bf16 v[138:141], v[102:105], v[178:181], v[138:141]
	v_mfma_f32_16x16x32_bf16 v[138:141], v[110:113], v[182:185], v[138:141]
	v_mfma_f32_16x16x32_bf16 v[126:129], v[90:93], v[192:195], v[126:129]
	v_mfma_f32_16x16x32_bf16 v[126:129], v[94:97], v[196:199], v[126:129]
	v_mfma_f32_16x16x32_bf16 v[122:125], v[102:105], v[192:195], v[122:125]
	v_mfma_f32_16x16x32_bf16 v[122:125], v[110:113], v[196:199], v[122:125]
	v_mfma_f32_16x16x32_bf16 v[106:109], v[90:93], v[200:203], v[106:109]
	v_mfma_f32_16x16x32_bf16 v[106:109], v[94:97], v[204:207], v[106:109]
	v_mfma_f32_16x16x32_bf16 v[98:101], v[102:105], v[200:203], v[98:101]
	v_mfma_f32_16x16x32_bf16 v[98:101], v[110:113], v[204:207], v[98:101]
	v_mfma_f32_16x16x32_bf16 v[78:81], v[90:93], v[208:211], v[78:81]
	v_mfma_f32_16x16x32_bf16 v[78:81], v[94:97], v[212:215], v[78:81]
	v_mfma_f32_16x16x32_bf16 v[74:77], v[102:105], v[208:211], v[74:77]
	v_mfma_f32_16x16x32_bf16 v[74:77], v[110:113], v[212:215], v[74:77]
	v_mfma_f32_16x16x32_bf16 v[134:137], v[146:149], v[178:181], v[134:137]
	v_mfma_f32_16x16x32_bf16 v[134:137], v[150:153], v[182:185], v[134:137]
	v_mfma_f32_16x16x32_bf16 v[130:133], v[154:157], v[178:181], v[130:133]
	v_mfma_f32_16x16x32_bf16 v[130:133], v[158:161], v[182:185], v[130:133]
	v_mfma_f32_16x16x32_bf16 v[118:121], v[146:149], v[192:195], v[118:121]
	v_mfma_f32_16x16x32_bf16 v[118:121], v[150:153], v[196:199], v[118:121]
	v_mfma_f32_16x16x32_bf16 v[114:117], v[154:157], v[192:195], v[114:117]
	v_mfma_f32_16x16x32_bf16 v[114:117], v[158:161], v[196:199], v[114:117]
	v_mfma_f32_16x16x32_bf16 v[86:89], v[146:149], v[200:203], v[86:89]
	v_mfma_f32_16x16x32_bf16 v[86:89], v[150:153], v[204:207], v[86:89]
	v_mfma_f32_16x16x32_bf16 v[82:85], v[154:157], v[200:203], v[82:85]
	v_mfma_f32_16x16x32_bf16 v[82:85], v[158:161], v[204:207], v[82:85]
	s_add_i32 s34, s52, s33
	s_mov_b32 m0, s34
	v_mfma_f32_16x16x32_bf16 v[70:73], v[146:149], v[208:211], v[70:73]
	v_mfma_f32_16x16x32_bf16 v[70:73], v[150:153], v[212:215], v[70:73]
	s_add_u32 s30, s30, 0x80
	s_addc_u32 s31, s31, 0
	v_mfma_f32_16x16x32_bf16 v[66:69], v[154:157], v[208:211], v[66:69]
	v_mfma_f32_16x16x32_bf16 v[66:69], v[158:161], v[212:215], v[66:69]
	s_barrier
	ds_read_b128 v[178:181], v190 offset:49152
	ds_read_b128 v[182:185], v190 offset:50176
	ds_read_b128 v[192:195], v190 offset:51200
	ds_read_b128 v[196:199], v190 offset:52224
	ds_read_b128 v[200:203], v190 offset:53248
	ds_read_b128 v[204:207], v190 offset:54272
	ds_read_b128 v[208:211], v190 offset:55296
	ds_read_b128 v[212:215], v190 offset:56320
	global_load_lds_dwordx4 v164, s[30:31]
	s_add_i32 m0, s34, 0x2000
	s_add_i32 s34, s53, s33
	global_load_lds_dwordx4 v168, s[30:31]
	s_add_u32 s30, s30, 0x100000
	s_addc_u32 s31, s31, 0
	s_mov_b32 m0, s34
	s_nop 0
	global_load_lds_dwordx4 v164, s[30:31]
	s_add_i32 m0, s34, 0x2000
	s_nop 0
	global_load_lds_dwordx4 v168, s[30:31]
	s_mov_b32 m0, s43
	s_nop 0
	global_load_lds_dwordx4 v162, s[98:99]
	s_mov_b32 m0, s44
	s_nop 0
	global_load_lds_dwordx4 v166, s[98:99]
	s_waitcnt vmcnt(8)
	s_waitcnt lgkmcnt(0)
	s_barrier
	v_mfma_f32_16x16x32_bf16 v[62:65], v[90:93], v[178:181], v[62:65]
	v_mfma_f32_16x16x32_bf16 v[62:65], v[94:97], v[182:185], v[62:65]
	v_mfma_f32_16x16x32_bf16 v[58:61], v[102:105], v[178:181], v[58:61]
	v_mfma_f32_16x16x32_bf16 v[58:61], v[110:113], v[182:185], v[58:61]
	v_mfma_f32_16x16x32_bf16 v[46:49], v[90:93], v[192:195], v[46:49]
	v_mfma_f32_16x16x32_bf16 v[46:49], v[94:97], v[196:199], v[46:49]
	v_mfma_f32_16x16x32_bf16 v[42:45], v[102:105], v[192:195], v[42:45]
	v_mfma_f32_16x16x32_bf16 v[42:45], v[110:113], v[196:199], v[42:45]
	v_mfma_f32_16x16x32_bf16 v[30:33], v[90:93], v[200:203], v[30:33]
	v_mfma_f32_16x16x32_bf16 v[30:33], v[94:97], v[204:207], v[30:33]
	v_mfma_f32_16x16x32_bf16 v[26:29], v[102:105], v[200:203], v[26:29]
	v_mfma_f32_16x16x32_bf16 v[26:29], v[110:113], v[204:207], v[26:29]
	v_mfma_f32_16x16x32_bf16 v[14:17], v[90:93], v[208:211], v[14:17]
	v_mfma_f32_16x16x32_bf16 v[14:17], v[94:97], v[212:215], v[14:17]
	v_mfma_f32_16x16x32_bf16 v[10:13], v[102:105], v[208:211], v[10:13]
	v_mfma_f32_16x16x32_bf16 v[10:13], v[110:113], v[212:215], v[10:13]
	v_mfma_f32_16x16x32_bf16 v[54:57], v[146:149], v[178:181], v[54:57]
	v_mfma_f32_16x16x32_bf16 v[54:57], v[150:153], v[182:185], v[54:57]
	v_mfma_f32_16x16x32_bf16 v[50:53], v[154:157], v[178:181], v[50:53]
	v_mfma_f32_16x16x32_bf16 v[50:53], v[158:161], v[182:185], v[50:53]
	v_mfma_f32_16x16x32_bf16 v[38:41], v[146:149], v[192:195], v[38:41]
	v_mfma_f32_16x16x32_bf16 v[38:41], v[150:153], v[196:199], v[38:41]
	v_mfma_f32_16x16x32_bf16 v[34:37], v[154:157], v[192:195], v[34:37]
	v_mfma_f32_16x16x32_bf16 v[34:37], v[158:161], v[196:199], v[34:37]
	v_mfma_f32_16x16x32_bf16 v[22:25], v[146:149], v[200:203], v[22:25]
	v_mfma_f32_16x16x32_bf16 v[22:25], v[150:153], v[204:207], v[22:25]
	s_add_i32 s51, s51, 2
	s_add_u32 s28, s28, 0x100
	v_mfma_f32_16x16x32_bf16 v[18:21], v[154:157], v[200:203], v[18:21]
	v_mfma_f32_16x16x32_bf16 v[18:21], v[158:161], v[204:207], v[18:21]
	s_addc_u32 s29, s29, 0
	s_add_u32 s49, s49, 0x100
	v_mfma_f32_16x16x32_bf16 v[6:9], v[146:149], v[208:211], v[6:9]
	v_mfma_f32_16x16x32_bf16 v[6:9], v[150:153], v[212:215], v[6:9]
	s_addc_u32 s50, s50, 0
	s_cmp_gt_u32 s51, 61
	v_mfma_f32_16x16x32_bf16 v[2:5], v[154:157], v[208:211], v[2:5]
	v_mfma_f32_16x16x32_bf16 v[2:5], v[158:161], v[212:215], v[2:5]
	s_barrier
	s_cbranch_scc0 .LBB0_941
	s_and_b64 vcc, exec, s[16:17]
	s_cbranch_vccz .LBB0_944
	s_barrier

.LBB0_1153:
	v_add_u32_e32 v146, s78, v187
	v_add_u32_e32 v162, s79, v187
	s_add_u32 s98, s46, s10
	s_addc_u32 s99, s47, s11
	s_add_u32 s98, s98, 0x100080
	s_addc_u32 s99, s99, 0
	s_add_u32 s56, s46, s10
	ds_read_b128 v[134:137], v146
	ds_read_b128 v[138:141], v146 offset:1024
	ds_read_b128 v[142:145], v146 offset:2048
	ds_read_b128 v[146:149], v146 offset:3072
	ds_read_b128 v[150:153], v162
	ds_read_b128 v[154:157], v162 offset:1024
	ds_read_b128 v[158:161], v162 offset:2048
	ds_read_b128 v[162:165], v162 offset:3072
	s_addc_u32 s57, s47, s11
	s_add_u32 s56, s56, 0x100
	s_addc_u32 s57, s57, 0
	s_add_u32 s84, s33, s10
	s_addc_u32 s85, s72, s11
	s_cmpk_eq_i32 s10, 0x1f00
	s_cselect_b32 s59, s29, s57
	s_cselect_b32 s58, s45, s56
	s_cselect_b32 s57, s43, s85
	s_cselect_b32 s56, s73, s84
	s_add_i32 m0, s64, 0xc000
	ds_read_b128 v[166:169], v230
	ds_read_b128 v[170:173], v230 offset:1024
	ds_read_b128 v[174:177], v230 offset:2048
	ds_read_b128 v[202:205], v230 offset:3072
	ds_read_b128 v[206:209], v230 offset:4096
	ds_read_b128 v[210:213], v230 offset:5120
	ds_read_b128 v[214:217], v230 offset:6144
	ds_read_b128 v[218:221], v230 offset:7168
	global_load_lds_dwordx4 v178, s[98:99]
	s_add_i32 m0, s64, 0xe000
	s_nop 0
	global_load_lds_dwordx4 v182, s[98:99]
	s_waitcnt vmcnt(8)
	s_waitcnt lgkmcnt(0)
	s_barrier
	v_mfma_f32_16x16x32_bf16 v[2:5], v[134:137], v[166:169], v[2:5]
	v_mfma_f32_16x16x32_bf16 v[2:5], v[138:141], v[170:173], v[2:5]
	v_mfma_f32_16x16x32_bf16 v[126:129], v[142:145], v[166:169], v[126:129]
	v_mfma_f32_16x16x32_bf16 v[126:129], v[146:149], v[170:173], v[126:129]
	v_mfma_f32_16x16x32_bf16 v[122:125], v[134:137], v[174:177], v[122:125]
	v_mfma_f32_16x16x32_bf16 v[122:125], v[138:141], v[202:205], v[122:125]
	v_mfma_f32_16x16x32_bf16 v[118:121], v[142:145], v[174:177], v[118:121]
	v_mfma_f32_16x16x32_bf16 v[118:121], v[146:149], v[202:205], v[118:121]
	v_mfma_f32_16x16x32_bf16 v[114:117], v[134:137], v[206:209], v[114:117]
	v_mfma_f32_16x16x32_bf16 v[114:117], v[138:141], v[210:213], v[114:117]
	v_mfma_f32_16x16x32_bf16 v[110:113], v[142:145], v[206:209], v[110:113]
	v_mfma_f32_16x16x32_bf16 v[110:113], v[146:149], v[210:213], v[110:113]
	v_mfma_f32_16x16x32_bf16 v[106:109], v[134:137], v[214:217], v[106:109]
	v_mfma_f32_16x16x32_bf16 v[106:109], v[138:141], v[218:221], v[106:109]
	v_mfma_f32_16x16x32_bf16 v[102:105], v[142:145], v[214:217], v[102:105]
	v_mfma_f32_16x16x32_bf16 v[102:105], v[146:149], v[218:221], v[102:105]
	v_mfma_f32_16x16x32_bf16 v[98:101], v[150:153], v[166:169], v[98:101]
	v_mfma_f32_16x16x32_bf16 v[98:101], v[154:157], v[170:173], v[98:101]
	v_mfma_f32_16x16x32_bf16 v[94:97], v[158:161], v[166:169], v[94:97]
	v_mfma_f32_16x16x32_bf16 v[94:97], v[162:165], v[170:173], v[94:97]
	v_mfma_f32_16x16x32_bf16 v[90:93], v[150:153], v[174:177], v[90:93]
	v_mfma_f32_16x16x32_bf16 v[90:93], v[154:157], v[202:205], v[90:93]
	v_mfma_f32_16x16x32_bf16 v[86:89], v[158:161], v[174:177], v[86:89]
	v_mfma_f32_16x16x32_bf16 v[86:89], v[162:165], v[202:205], v[86:89]
	v_mfma_f32_16x16x32_bf16 v[82:85], v[150:153], v[206:209], v[82:85]
	v_mfma_f32_16x16x32_bf16 v[82:85], v[154:157], v[210:213], v[82:85]
	v_mfma_f32_16x16x32_bf16 v[78:81], v[158:161], v[206:209], v[78:81]
	v_mfma_f32_16x16x32_bf16 v[78:81], v[162:165], v[210:213], v[78:81]
	v_mfma_f32_16x16x32_bf16 v[74:77], v[150:153], v[214:217], v[74:77]
	v_mfma_f32_16x16x32_bf16 v[74:77], v[154:157], v[218:221], v[74:77]
	s_add_i32 s84, s78, s63
	s_mov_b32 m0, s84
	v_mfma_f32_16x16x32_bf16 v[70:73], v[158:161], v[214:217], v[70:73]
	v_mfma_f32_16x16x32_bf16 v[70:73], v[162:165], v[218:221], v[70:73]
	s_barrier
	ds_read_b128 v[166:169], v230 offset:16384
	ds_read_b128 v[170:173], v230 offset:17408
	ds_read_b128 v[174:177], v230 offset:18432
	ds_read_b128 v[202:205], v230 offset:19456
	ds_read_b128 v[206:209], v230 offset:20480
	ds_read_b128 v[210:213], v230 offset:21504
	ds_read_b128 v[214:217], v230 offset:22528
	ds_read_b128 v[218:221], v230 offset:23552
	global_load_lds_dwordx4 v180, s[56:57]
	s_add_i32 m0, s84, 0x2000
	s_add_u32 s84, s56, 0x100000
	s_addc_u32 s85, s57, 0
	s_add_i32 s86, s79, s63
	global_load_lds_dwordx4 v184, s[56:57]
	s_mov_b32 m0, s86
	s_nop 0
	global_load_lds_dwordx4 v180, s[84:85]
	s_add_i32 m0, s86, 0x2000
	s_nop 0
	global_load_lds_dwordx4 v184, s[84:85]
	s_mov_b32 m0, s64
	s_nop 0
	global_load_lds_dwordx4 v178, s[58:59]
	s_mov_b32 m0, s65
	s_nop 0
	global_load_lds_dwordx4 v182, s[58:59]
	s_waitcnt vmcnt(8)
	s_waitcnt lgkmcnt(0)
	s_barrier
	v_mfma_f32_16x16x32_bf16 v[66:69], v[134:137], v[166:169], v[66:69]
	v_mfma_f32_16x16x32_bf16 v[66:69], v[138:141], v[170:173], v[66:69]
	v_mfma_f32_16x16x32_bf16 v[62:65], v[142:145], v[166:169], v[62:65]
	v_mfma_f32_16x16x32_bf16 v[62:65], v[146:149], v[170:173], v[62:65]
	v_mfma_f32_16x16x32_bf16 v[58:61], v[134:137], v[174:177], v[58:61]
	v_mfma_f32_16x16x32_bf16 v[58:61], v[138:141], v[202:205], v[58:61]
	v_mfma_f32_16x16x32_bf16 v[54:57], v[142:145], v[174:177], v[54:57]
	v_mfma_f32_16x16x32_bf16 v[54:57], v[146:149], v[202:205], v[54:57]
	v_mfma_f32_16x16x32_bf16 v[50:53], v[134:137], v[206:209], v[50:53]
	v_mfma_f32_16x16x32_bf16 v[50:53], v[138:141], v[210:213], v[50:53]
	v_mfma_f32_16x16x32_bf16 v[46:49], v[142:145], v[206:209], v[46:49]
	v_mfma_f32_16x16x32_bf16 v[46:49], v[146:149], v[210:213], v[46:49]
	v_mfma_f32_16x16x32_bf16 v[42:45], v[134:137], v[214:217], v[42:45]
	v_mfma_f32_16x16x32_bf16 v[42:45], v[138:141], v[218:221], v[42:45]
	v_mfma_f32_16x16x32_bf16 v[38:41], v[142:145], v[214:217], v[38:41]
	v_mfma_f32_16x16x32_bf16 v[38:41], v[146:149], v[218:221], v[38:41]
	v_mfma_f32_16x16x32_bf16 v[34:37], v[150:153], v[166:169], v[34:37]
	v_mfma_f32_16x16x32_bf16 v[34:37], v[154:157], v[170:173], v[34:37]
	v_mfma_f32_16x16x32_bf16 v[30:33], v[158:161], v[166:169], v[30:33]
	v_mfma_f32_16x16x32_bf16 v[30:33], v[162:165], v[170:173], v[30:33]
	v_mfma_f32_16x16x32_bf16 v[26:29], v[150:153], v[174:177], v[26:29]
	v_mfma_f32_16x16x32_bf16 v[26:29], v[154:157], v[202:205], v[26:29]
	v_mfma_f32_16x16x32_bf16 v[22:25], v[158:161], v[174:177], v[22:25]
	v_mfma_f32_16x16x32_bf16 v[22:25], v[162:165], v[202:205], v[22:25]
	s_add_i32 s84, 0, 0x18000
	s_add_i32 s85, 0, 0x1c000
	v_mfma_f32_16x16x32_bf16 v[18:21], v[150:153], v[206:209], v[18:21]
	v_mfma_f32_16x16x32_bf16 v[18:21], v[154:157], v[210:213], v[18:21]
	s_add_u32 s100, s58, 0x80
	s_addc_u32 s101, s59, 0
	v_mfma_f32_16x16x32_bf16 v[14:17], v[158:161], v[206:209], v[14:17]
	v_mfma_f32_16x16x32_bf16 v[14:17], v[162:165], v[210:213], v[14:17]
	s_add_u32 s58, s58, 0x100000
	s_addc_u32 s59, s59, 0
	v_mfma_f32_16x16x32_bf16 v[10:13], v[150:153], v[214:217], v[10:13]
	v_mfma_f32_16x16x32_bf16 v[10:13], v[154:157], v[218:221], v[10:13]
	s_mov_b32 m0, s67
	v_mfma_f32_16x16x32_bf16 v[6:9], v[158:161], v[214:217], v[6:9]
	v_mfma_f32_16x16x32_bf16 v[6:9], v[162:165], v[218:221], v[6:9]
	s_barrier
	ds_read_b128 v[134:137], v246
	ds_read_b128 v[138:141], v246 offset:1024
	ds_read_b128 v[142:145], v246 offset:2048
	ds_read_b128 v[146:149], v246 offset:3072
	ds_read_b128 v[150:153], v247
	ds_read_b128 v[154:157], v247 offset:1024
	ds_read_b128 v[158:161], v247 offset:2048
	ds_read_b128 v[162:165], v247 offset:3072
	ds_read_b128 v[166:169], v230 offset:32768
	ds_read_b128 v[170:173], v230 offset:33792
	ds_read_b128 v[174:177], v230 offset:34816
	ds_read_b128 v[202:205], v230 offset:35840
	ds_read_b128 v[206:209], v230 offset:36864
	ds_read_b128 v[210:213], v230 offset:37888
	ds_read_b128 v[214:217], v230 offset:38912
	ds_read_b128 v[218:221], v230 offset:39936
	global_load_lds_dwordx4 v178, s[58:59]
	s_mov_b32 m0, s68
	s_nop 0
	global_load_lds_dwordx4 v182, s[58:59]
	s_waitcnt vmcnt(8)
	s_waitcnt lgkmcnt(0)
	s_barrier
	v_mfma_f32_16x16x32_bf16 v[2:5], v[134:137], v[166:169], v[2:5]
	v_mfma_f32_16x16x32_bf16 v[2:5], v[138:141], v[170:173], v[2:5]
	v_mfma_f32_16x16x32_bf16 v[126:129], v[142:145], v[166:169], v[126:129]
	v_mfma_f32_16x16x32_bf16 v[126:129], v[146:149], v[170:173], v[126:129]
	v_mfma_f32_16x16x32_bf16 v[122:125], v[134:137], v[174:177], v[122:125]
	v_mfma_f32_16x16x32_bf16 v[122:125], v[138:141], v[202:205], v[122:125]
	v_mfma_f32_16x16x32_bf16 v[118:121], v[142:145], v[174:177], v[118:121]
	v_mfma_f32_16x16x32_bf16 v[118:121], v[146:149], v[202:205], v[118:121]
	v_mfma_f32_16x16x32_bf16 v[114:117], v[134:137], v[206:209], v[114:117]
	v_mfma_f32_16x16x32_bf16 v[114:117], v[138:141], v[210:213], v[114:117]
	v_mfma_f32_16x16x32_bf16 v[110:113], v[142:145], v[206:209], v[110:113]
	v_mfma_f32_16x16x32_bf16 v[110:113], v[146:149], v[210:213], v[110:113]
	v_mfma_f32_16x16x32_bf16 v[106:109], v[134:137], v[214:217], v[106:109]
	v_mfma_f32_16x16x32_bf16 v[106:109], v[138:141], v[218:221], v[106:109]
	v_mfma_f32_16x16x32_bf16 v[102:105], v[142:145], v[214:217], v[102:105]
	v_mfma_f32_16x16x32_bf16 v[102:105], v[146:149], v[218:221], v[102:105]
	v_mfma_f32_16x16x32_bf16 v[98:101], v[150:153], v[166:169], v[98:101]
	v_mfma_f32_16x16x32_bf16 v[98:101], v[154:157], v[170:173], v[98:101]
	v_mfma_f32_16x16x32_bf16 v[94:97], v[158:161], v[166:169], v[94:97]
	v_mfma_f32_16x16x32_bf16 v[94:97], v[162:165], v[170:173], v[94:97]
	v_mfma_f32_16x16x32_bf16 v[90:93], v[150:153], v[174:177], v[90:93]
	v_mfma_f32_16x16x32_bf16 v[90:93], v[154:157], v[202:205], v[90:93]
	v_mfma_f32_16x16x32_bf16 v[86:89], v[158:161], v[174:177], v[86:89]
	v_mfma_f32_16x16x32_bf16 v[86:89], v[162:165], v[202:205], v[86:89]
	v_mfma_f32_16x16x32_bf16 v[82:85], v[150:153], v[206:209], v[82:85]
	v_mfma_f32_16x16x32_bf16 v[82:85], v[154:157], v[210:213], v[82:85]
	v_mfma_f32_16x16x32_bf16 v[78:81], v[158:161], v[206:209], v[78:81]
	v_mfma_f32_16x16x32_bf16 v[78:81], v[162:165], v[210:213], v[78:81]
	s_add_i32 s58, s84, s63
	s_add_u32 s98, s56, 0x80
	v_mfma_f32_16x16x32_bf16 v[74:77], v[150:153], v[214:217], v[74:77]
	v_mfma_f32_16x16x32_bf16 v[74:77], v[154:157], v[218:221], v[74:77]
	s_addc_u32 s99, s57, 0
	s_mov_b32 m0, s58
	v_mfma_f32_16x16x32_bf16 v[70:73], v[158:161], v[214:217], v[70:73]
	v_mfma_f32_16x16x32_bf16 v[70:73], v[162:165], v[218:221], v[70:73]
	s_barrier
	ds_read_b128 v[166:169], v230 offset:49152
	ds_read_b128 v[170:173], v230 offset:50176
	ds_read_b128 v[174:177], v230 offset:51200
	ds_read_b128 v[202:205], v230 offset:52224
	ds_read_b128 v[206:209], v230 offset:53248
	ds_read_b128 v[210:213], v230 offset:54272
	ds_read_b128 v[214:217], v230 offset:55296
	ds_read_b128 v[218:221], v230 offset:56320
	global_load_lds_dwordx4 v180, s[98:99]
	s_add_i32 m0, s58, 0x2000
	s_add_u32 s56, s56, 0x100080
	s_addc_u32 s57, s57, 0
	s_add_i32 s58, s85, s63
	global_load_lds_dwordx4 v184, s[98:99]
	s_mov_b32 m0, s58
	s_nop 0
	global_load_lds_dwordx4 v180, s[56:57]
	s_add_i32 m0, s58, 0x2000
	s_nop 0
	global_load_lds_dwordx4 v184, s[56:57]
	s_mov_b32 m0, s74
	s_nop 0
	global_load_lds_dwordx4 v178, s[100:101]
	s_mov_b32 m0, s75
	s_nop 0
	global_load_lds_dwordx4 v182, s[100:101]
	s_waitcnt vmcnt(8)
	s_waitcnt lgkmcnt(0)
	s_barrier
	v_mfma_f32_16x16x32_bf16 v[66:69], v[134:137], v[166:169], v[66:69]
	v_mfma_f32_16x16x32_bf16 v[66:69], v[138:141], v[170:173], v[66:69]
	v_mfma_f32_16x16x32_bf16 v[62:65], v[142:145], v[166:169], v[62:65]
	v_mfma_f32_16x16x32_bf16 v[62:65], v[146:149], v[170:173], v[62:65]
	v_mfma_f32_16x16x32_bf16 v[58:61], v[134:137], v[174:177], v[58:61]
	v_mfma_f32_16x16x32_bf16 v[58:61], v[138:141], v[202:205], v[58:61]
	v_mfma_f32_16x16x32_bf16 v[54:57], v[142:145], v[174:177], v[54:57]
	v_mfma_f32_16x16x32_bf16 v[54:57], v[146:149], v[202:205], v[54:57]
	v_mfma_f32_16x16x32_bf16 v[50:53], v[134:137], v[206:209], v[50:53]
	v_mfma_f32_16x16x32_bf16 v[50:53], v[138:141], v[210:213], v[50:53]
	v_mfma_f32_16x16x32_bf16 v[46:49], v[142:145], v[206:209], v[46:49]
	v_mfma_f32_16x16x32_bf16 v[46:49], v[146:149], v[210:213], v[46:49]
	v_mfma_f32_16x16x32_bf16 v[42:45], v[134:137], v[214:217], v[42:45]
	v_mfma_f32_16x16x32_bf16 v[42:45], v[138:141], v[218:221], v[42:45]
	v_mfma_f32_16x16x32_bf16 v[38:41], v[142:145], v[214:217], v[38:41]
	v_mfma_f32_16x16x32_bf16 v[38:41], v[146:149], v[218:221], v[38:41]
	v_mfma_f32_16x16x32_bf16 v[34:37], v[150:153], v[166:169], v[34:37]
	v_mfma_f32_16x16x32_bf16 v[34:37], v[154:157], v[170:173], v[34:37]
	v_mfma_f32_16x16x32_bf16 v[30:33], v[158:161], v[166:169], v[30:33]
	v_mfma_f32_16x16x32_bf16 v[30:33], v[162:165], v[170:173], v[30:33]
	v_mfma_f32_16x16x32_bf16 v[26:29], v[150:153], v[174:177], v[26:29]
	v_mfma_f32_16x16x32_bf16 v[26:29], v[154:157], v[202:205], v[26:29]
	v_mfma_f32_16x16x32_bf16 v[22:25], v[158:161], v[174:177], v[22:25]
	v_mfma_f32_16x16x32_bf16 v[22:25], v[162:165], v[202:205], v[22:25]
	v_mfma_f32_16x16x32_bf16 v[18:21], v[150:153], v[206:209], v[18:21]
	v_mfma_f32_16x16x32_bf16 v[18:21], v[154:157], v[210:213], v[18:21]
	v_mfma_f32_16x16x32_bf16 v[14:17], v[158:161], v[206:209], v[14:17]
	v_mfma_f32_16x16x32_bf16 v[14:17], v[162:165], v[210:213], v[14:17]
	s_add_i32 s83, s83, 2
	s_add_u32 s10, s10, 0x100
	v_mfma_f32_16x16x32_bf16 v[10:13], v[150:153], v[214:217], v[10:13]
	v_mfma_f32_16x16x32_bf16 v[10:13], v[154:157], v[218:221], v[10:13]
	s_addc_u32 s11, s11, 0
	s_cmp_gt_u32 s83, 61
	v_mfma_f32_16x16x32_bf16 v[6:9], v[158:161], v[214:217], v[6:9]
	v_mfma_f32_16x16x32_bf16 v[6:9], v[162:165], v[218:221], v[6:9]
	s_barrier
	s_cbranch_scc0 .LBB0_1153
	s_and_b64 vcc, exec, s[36:37]
	s_cbranch_vccz .LBB0_1156
	s_barrier

.LBB0_1325:
	ds_read_b128 v[130:133], v176
	ds_read_b128 v[134:137], v176 offset:1024
	ds_read_b128 v[138:141], v176 offset:2048
	ds_read_b128 v[142:145], v176 offset:3072
	ds_read_b128 v[146:149], v177
	ds_read_b128 v[166:169], v177 offset:1024
	ds_read_b128 v[170:173], v177 offset:2048
	ds_read_b128 v[180:183], v177 offset:3072
	s_add_u32 s26, s24, 0xffd50080
	s_addc_u32 s27, s25, -1
	s_cmpk_eq_i32 s49, 0xa8
	s_cselect_b32 s29, s5, s27
	s_cselect_b32 s28, s4, s26
	s_cselect_b32 s27, s23, s48
	s_cselect_b32 s26, s22, s47
	s_add_i32 m0, s33, 0xc000
	ds_read_b128 v[184:187], v178
	ds_read_b128 v[188:191], v178 offset:1024
	ds_read_b128 v[192:195], v178 offset:2048
	ds_read_b128 v[196:199], v178 offset:3072
	ds_read_b128 v[200:203], v178 offset:4096
	ds_read_b128 v[204:207], v178 offset:5120
	ds_read_b128 v[208:211], v178 offset:6144
	ds_read_b128 v[212:215], v178 offset:7168
	global_load_lds_dwordx4 v158, s[24:25]
	s_add_i32 m0, s33, 0xe000
	s_nop 0
	global_load_lds_dwordx4 v160, s[24:25]
	s_waitcnt vmcnt(8)
	s_waitcnt lgkmcnt(0)
	s_barrier
	v_mfma_f32_16x16x32_bf16 v[126:129], v[130:133], v[184:187], v[126:129]
	v_mfma_f32_16x16x32_bf16 v[126:129], v[134:137], v[188:191], v[126:129]
	v_mfma_f32_16x16x32_bf16 v[122:125], v[138:141], v[184:187], v[122:125]
	v_mfma_f32_16x16x32_bf16 v[122:125], v[142:145], v[188:191], v[122:125]
	v_mfma_f32_16x16x32_bf16 v[110:113], v[130:133], v[192:195], v[110:113]
	v_mfma_f32_16x16x32_bf16 v[110:113], v[134:137], v[196:199], v[110:113]
	v_mfma_f32_16x16x32_bf16 v[106:109], v[138:141], v[192:195], v[106:109]
	v_mfma_f32_16x16x32_bf16 v[106:109], v[142:145], v[196:199], v[106:109]
	v_mfma_f32_16x16x32_bf16 v[94:97], v[130:133], v[200:203], v[94:97]
	v_mfma_f32_16x16x32_bf16 v[94:97], v[134:137], v[204:207], v[94:97]
	v_mfma_f32_16x16x32_bf16 v[90:93], v[138:141], v[200:203], v[90:93]
	v_mfma_f32_16x16x32_bf16 v[90:93], v[142:145], v[204:207], v[90:93]
	v_mfma_f32_16x16x32_bf16 v[78:81], v[130:133], v[208:211], v[78:81]
	v_mfma_f32_16x16x32_bf16 v[78:81], v[134:137], v[212:215], v[78:81]
	v_mfma_f32_16x16x32_bf16 v[74:77], v[138:141], v[208:211], v[74:77]
	v_mfma_f32_16x16x32_bf16 v[74:77], v[142:145], v[212:215], v[74:77]
	v_mfma_f32_16x16x32_bf16 v[118:121], v[146:149], v[184:187], v[118:121]
	v_mfma_f32_16x16x32_bf16 v[118:121], v[166:169], v[188:191], v[118:121]
	v_mfma_f32_16x16x32_bf16 v[114:117], v[170:173], v[184:187], v[114:117]
	v_mfma_f32_16x16x32_bf16 v[114:117], v[180:183], v[188:191], v[114:117]
	v_mfma_f32_16x16x32_bf16 v[102:105], v[146:149], v[192:195], v[102:105]
	v_mfma_f32_16x16x32_bf16 v[102:105], v[166:169], v[196:199], v[102:105]
	v_mfma_f32_16x16x32_bf16 v[98:101], v[170:173], v[192:195], v[98:101]
	v_mfma_f32_16x16x32_bf16 v[98:101], v[180:183], v[196:199], v[98:101]
	v_mfma_f32_16x16x32_bf16 v[86:89], v[146:149], v[200:203], v[86:89]
	v_mfma_f32_16x16x32_bf16 v[86:89], v[166:169], v[204:207], v[86:89]
	v_mfma_f32_16x16x32_bf16 v[82:85], v[170:173], v[200:203], v[82:85]
	v_mfma_f32_16x16x32_bf16 v[82:85], v[180:183], v[204:207], v[82:85]
	v_mfma_f32_16x16x32_bf16 v[70:73], v[146:149], v[208:211], v[70:73]
	v_mfma_f32_16x16x32_bf16 v[70:73], v[166:169], v[212:215], v[70:73]
	s_add_i32 s50, s41, s31
	s_mov_b32 m0, s50
	v_mfma_f32_16x16x32_bf16 v[66:69], v[170:173], v[208:211], v[66:69]
	v_mfma_f32_16x16x32_bf16 v[66:69], v[180:183], v[212:215], v[66:69]
	s_barrier
	ds_read_b128 v[184:187], v178 offset:16384
	ds_read_b128 v[188:191], v178 offset:17408
	ds_read_b128 v[192:195], v178 offset:18432
	ds_read_b128 v[196:199], v178 offset:19456
	ds_read_b128 v[200:203], v178 offset:20480
	ds_read_b128 v[204:207], v178 offset:21504
	ds_read_b128 v[208:211], v178 offset:22528
	ds_read_b128 v[212:215], v178 offset:23552
	global_load_lds_dwordx4 v152, s[26:27]
	s_add_i32 m0, s50, 0x2000
	s_add_u32 s50, s26, 0x2b0000
	s_addc_u32 s51, s27, 0
	s_add_i32 s52, s42, s31
	global_load_lds_dwordx4 v156, s[26:27]
	s_mov_b32 m0, s52
	global_load_lds_dwordx4 v152, s[50:51]
	s_add_i32 m0, s52, 0x2000
	s_nop 0
	global_load_lds_dwordx4 v156, s[50:51]
	s_mov_b32 m0, s33
	s_nop 0
	global_load_lds_dwordx4 v150, s[28:29]
	s_mov_b32 m0, s34
	s_nop 0
	global_load_lds_dwordx4 v154, s[28:29]
	s_waitcnt vmcnt(8)
	s_waitcnt lgkmcnt(0)
	s_barrier
	v_mfma_f32_16x16x32_bf16 v[62:65], v[130:133], v[184:187], v[62:65]
	v_mfma_f32_16x16x32_bf16 v[62:65], v[134:137], v[188:191], v[62:65]
	v_mfma_f32_16x16x32_bf16 v[58:61], v[138:141], v[184:187], v[58:61]
	v_mfma_f32_16x16x32_bf16 v[58:61], v[142:145], v[188:191], v[58:61]
	v_mfma_f32_16x16x32_bf16 v[46:49], v[130:133], v[192:195], v[46:49]
	v_mfma_f32_16x16x32_bf16 v[46:49], v[134:137], v[196:199], v[46:49]
	v_mfma_f32_16x16x32_bf16 v[42:45], v[138:141], v[192:195], v[42:45]
	v_mfma_f32_16x16x32_bf16 v[42:45], v[142:145], v[196:199], v[42:45]
	v_mfma_f32_16x16x32_bf16 v[30:33], v[130:133], v[200:203], v[30:33]
	v_mfma_f32_16x16x32_bf16 v[30:33], v[134:137], v[204:207], v[30:33]
	v_mfma_f32_16x16x32_bf16 v[26:29], v[138:141], v[200:203], v[26:29]
	v_mfma_f32_16x16x32_bf16 v[26:29], v[142:145], v[204:207], v[26:29]
	v_mfma_f32_16x16x32_bf16 v[14:17], v[130:133], v[208:211], v[14:17]
	v_mfma_f32_16x16x32_bf16 v[14:17], v[134:137], v[212:215], v[14:17]
	v_mfma_f32_16x16x32_bf16 v[10:13], v[138:141], v[208:211], v[10:13]
	v_mfma_f32_16x16x32_bf16 v[10:13], v[142:145], v[212:215], v[10:13]
	v_mfma_f32_16x16x32_bf16 v[54:57], v[146:149], v[184:187], v[54:57]
	v_mfma_f32_16x16x32_bf16 v[54:57], v[166:169], v[188:191], v[54:57]
	v_mfma_f32_16x16x32_bf16 v[50:53], v[170:173], v[184:187], v[50:53]
	v_mfma_f32_16x16x32_bf16 v[50:53], v[180:183], v[188:191], v[50:53]
	v_mfma_f32_16x16x32_bf16 v[38:41], v[146:149], v[192:195], v[38:41]
	v_mfma_f32_16x16x32_bf16 v[38:41], v[166:169], v[196:199], v[38:41]
	v_mfma_f32_16x16x32_bf16 v[34:37], v[170:173], v[192:195], v[34:37]
	v_mfma_f32_16x16x32_bf16 v[34:37], v[180:183], v[196:199], v[34:37]
	s_add_i32 s50, 0, 0x18000
	s_add_i32 s51, 0, 0x1c000
	v_mfma_f32_16x16x32_bf16 v[22:25], v[146:149], v[200:203], v[22:25]
	v_mfma_f32_16x16x32_bf16 v[22:25], v[166:169], v[204:207], v[22:25]
	s_add_u32 s98, s28, 0x80
	s_addc_u32 s99, s29, 0
	v_mfma_f32_16x16x32_bf16 v[18:21], v[170:173], v[200:203], v[18:21]
	v_mfma_f32_16x16x32_bf16 v[18:21], v[180:183], v[204:207], v[18:21]
	s_add_u32 s28, s28, 0x2b0000
	s_addc_u32 s29, s29, 0
	v_mfma_f32_16x16x32_bf16 v[6:9], v[146:149], v[208:211], v[6:9]
	v_mfma_f32_16x16x32_bf16 v[6:9], v[166:169], v[212:215], v[6:9]
	s_mov_b32 m0, s35
	v_mfma_f32_16x16x32_bf16 v[2:5], v[170:173], v[208:211], v[2:5]
	v_mfma_f32_16x16x32_bf16 v[2:5], v[180:183], v[212:215], v[2:5]
	s_barrier
	ds_read_b128 v[130:133], v246
	ds_read_b128 v[134:137], v246 offset:1024
	ds_read_b128 v[138:141], v246 offset:2048
	ds_read_b128 v[142:145], v246 offset:3072
	ds_read_b128 v[146:149], v247
	ds_read_b128 v[166:169], v247 offset:1024
	ds_read_b128 v[170:173], v247 offset:2048
	ds_read_b128 v[180:183], v247 offset:3072
	ds_read_b128 v[184:187], v178 offset:32768
	ds_read_b128 v[188:191], v178 offset:33792
	ds_read_b128 v[192:195], v178 offset:34816
	ds_read_b128 v[196:199], v178 offset:35840
	ds_read_b128 v[200:203], v178 offset:36864
	ds_read_b128 v[204:207], v178 offset:37888
	ds_read_b128 v[208:211], v178 offset:38912
	ds_read_b128 v[212:215], v178 offset:39936
	global_load_lds_dwordx4 v150, s[28:29]
	s_mov_b32 m0, s36
	s_nop 0
	global_load_lds_dwordx4 v154, s[28:29]
	s_waitcnt vmcnt(8)
	s_waitcnt lgkmcnt(0)
	s_barrier
	v_mfma_f32_16x16x32_bf16 v[126:129], v[130:133], v[184:187], v[126:129]
	v_mfma_f32_16x16x32_bf16 v[126:129], v[134:137], v[188:191], v[126:129]
	v_mfma_f32_16x16x32_bf16 v[122:125], v[138:141], v[184:187], v[122:125]
	v_mfma_f32_16x16x32_bf16 v[122:125], v[142:145], v[188:191], v[122:125]
	v_mfma_f32_16x16x32_bf16 v[110:113], v[130:133], v[192:195], v[110:113]
	v_mfma_f32_16x16x32_bf16 v[110:113], v[134:137], v[196:199], v[110:113]
	v_mfma_f32_16x16x32_bf16 v[106:109], v[138:141], v[192:195], v[106:109]
	v_mfma_f32_16x16x32_bf16 v[106:109], v[142:145], v[196:199], v[106:109]
	v_mfma_f32_16x16x32_bf16 v[94:97], v[130:133], v[200:203], v[94:97]
	v_mfma_f32_16x16x32_bf16 v[94:97], v[134:137], v[204:207], v[94:97]
	v_mfma_f32_16x16x32_bf16 v[90:93], v[138:141], v[200:203], v[90:93]
	v_mfma_f32_16x16x32_bf16 v[90:93], v[142:145], v[204:207], v[90:93]
	v_mfma_f32_16x16x32_bf16 v[78:81], v[130:133], v[208:211], v[78:81]
	v_mfma_f32_16x16x32_bf16 v[78:81], v[134:137], v[212:215], v[78:81]
	v_mfma_f32_16x16x32_bf16 v[74:77], v[138:141], v[208:211], v[74:77]
	v_mfma_f32_16x16x32_bf16 v[74:77], v[142:145], v[212:215], v[74:77]
	v_mfma_f32_16x16x32_bf16 v[118:121], v[146:149], v[184:187], v[118:121]
	v_mfma_f32_16x16x32_bf16 v[118:121], v[166:169], v[188:191], v[118:121]
	v_mfma_f32_16x16x32_bf16 v[114:117], v[170:173], v[184:187], v[114:117]
	v_mfma_f32_16x16x32_bf16 v[114:117], v[180:183], v[188:191], v[114:117]
	v_mfma_f32_16x16x32_bf16 v[102:105], v[146:149], v[192:195], v[102:105]
	v_mfma_f32_16x16x32_bf16 v[102:105], v[166:169], v[196:199], v[102:105]
	v_mfma_f32_16x16x32_bf16 v[98:101], v[170:173], v[192:195], v[98:101]
	v_mfma_f32_16x16x32_bf16 v[98:101], v[180:183], v[196:199], v[98:101]
	v_mfma_f32_16x16x32_bf16 v[86:89], v[146:149], v[200:203], v[86:89]
	v_mfma_f32_16x16x32_bf16 v[86:89], v[166:169], v[204:207], v[86:89]
	v_mfma_f32_16x16x32_bf16 v[82:85], v[170:173], v[200:203], v[82:85]
	v_mfma_f32_16x16x32_bf16 v[82:85], v[180:183], v[204:207], v[82:85]
	s_add_i32 s28, s50, s31
	s_mov_b32 m0, s28
	v_mfma_f32_16x16x32_bf16 v[70:73], v[146:149], v[208:211], v[70:73]
	v_mfma_f32_16x16x32_bf16 v[70:73], v[166:169], v[212:215], v[70:73]
	s_add_u32 s26, s26, 0x80
	s_addc_u32 s27, s27, 0
	v_mfma_f32_16x16x32_bf16 v[66:69], v[170:173], v[208:211], v[66:69]
	v_mfma_f32_16x16x32_bf16 v[66:69], v[180:183], v[212:215], v[66:69]
	s_barrier
	ds_read_b128 v[184:187], v178 offset:49152
	ds_read_b128 v[188:191], v178 offset:50176
	ds_read_b128 v[192:195], v178 offset:51200
	ds_read_b128 v[196:199], v178 offset:52224
	ds_read_b128 v[200:203], v178 offset:53248
	ds_read_b128 v[204:207], v178 offset:54272
	ds_read_b128 v[208:211], v178 offset:55296
	ds_read_b128 v[212:215], v178 offset:56320
	global_load_lds_dwordx4 v152, s[26:27]
	s_add_i32 m0, s28, 0x2000
	s_add_i32 s28, s51, s31
	global_load_lds_dwordx4 v156, s[26:27]
	s_add_u32 s26, s26, 0x2b0000
	s_addc_u32 s27, s27, 0
	s_mov_b32 m0, s28
	s_nop 0
	global_load_lds_dwordx4 v152, s[26:27]
	s_add_i32 m0, s28, 0x2000
	s_nop 0
	global_load_lds_dwordx4 v156, s[26:27]
	s_mov_b32 m0, s38
	s_nop 0
	global_load_lds_dwordx4 v150, s[98:99]
	s_mov_b32 m0, s39
	s_nop 0
	global_load_lds_dwordx4 v154, s[98:99]
	s_waitcnt vmcnt(8)
	s_waitcnt lgkmcnt(0)
	s_barrier
	v_mfma_f32_16x16x32_bf16 v[62:65], v[130:133], v[184:187], v[62:65]
	v_mfma_f32_16x16x32_bf16 v[62:65], v[134:137], v[188:191], v[62:65]
	v_mfma_f32_16x16x32_bf16 v[58:61], v[138:141], v[184:187], v[58:61]
	v_mfma_f32_16x16x32_bf16 v[58:61], v[142:145], v[188:191], v[58:61]
	v_mfma_f32_16x16x32_bf16 v[46:49], v[130:133], v[192:195], v[46:49]
	v_mfma_f32_16x16x32_bf16 v[46:49], v[134:137], v[196:199], v[46:49]
	v_mfma_f32_16x16x32_bf16 v[42:45], v[138:141], v[192:195], v[42:45]
	v_mfma_f32_16x16x32_bf16 v[42:45], v[142:145], v[196:199], v[42:45]
	v_mfma_f32_16x16x32_bf16 v[30:33], v[130:133], v[200:203], v[30:33]
	v_mfma_f32_16x16x32_bf16 v[30:33], v[134:137], v[204:207], v[30:33]
	v_mfma_f32_16x16x32_bf16 v[26:29], v[138:141], v[200:203], v[26:29]
	v_mfma_f32_16x16x32_bf16 v[26:29], v[142:145], v[204:207], v[26:29]
	v_mfma_f32_16x16x32_bf16 v[14:17], v[130:133], v[208:211], v[14:17]
	v_mfma_f32_16x16x32_bf16 v[14:17], v[134:137], v[212:215], v[14:17]
	v_mfma_f32_16x16x32_bf16 v[10:13], v[138:141], v[208:211], v[10:13]
	v_mfma_f32_16x16x32_bf16 v[10:13], v[142:145], v[212:215], v[10:13]
	v_mfma_f32_16x16x32_bf16 v[54:57], v[146:149], v[184:187], v[54:57]
	v_mfma_f32_16x16x32_bf16 v[54:57], v[166:169], v[188:191], v[54:57]
	v_mfma_f32_16x16x32_bf16 v[50:53], v[170:173], v[184:187], v[50:53]
	v_mfma_f32_16x16x32_bf16 v[50:53], v[180:183], v[188:191], v[50:53]
	v_mfma_f32_16x16x32_bf16 v[38:41], v[146:149], v[192:195], v[38:41]
	v_mfma_f32_16x16x32_bf16 v[38:41], v[166:169], v[196:199], v[38:41]
	v_mfma_f32_16x16x32_bf16 v[34:37], v[170:173], v[192:195], v[34:37]
	v_mfma_f32_16x16x32_bf16 v[34:37], v[180:183], v[196:199], v[34:37]
	v_mfma_f32_16x16x32_bf16 v[22:25], v[146:149], v[200:203], v[22:25]
	v_mfma_f32_16x16x32_bf16 v[22:25], v[166:169], v[204:207], v[22:25]
	s_add_i32 s49, s49, 2
	s_add_u32 s24, s24, 0x100
	v_mfma_f32_16x16x32_bf16 v[18:21], v[170:173], v[200:203], v[18:21]
	v_mfma_f32_16x16x32_bf16 v[18:21], v[180:183], v[204:207], v[18:21]
	s_addc_u32 s25, s25, 0
	s_add_u32 s47, s47, 0x100
	v_mfma_f32_16x16x32_bf16 v[6:9], v[146:149], v[208:211], v[6:9]
	v_mfma_f32_16x16x32_bf16 v[6:9], v[166:169], v[212:215], v[6:9]
	s_addc_u32 s48, s48, 0
	s_cmpk_gt_u32 s49, 0xa9
	v_mfma_f32_16x16x32_bf16 v[2:5], v[170:173], v[208:211], v[2:5]
	v_mfma_f32_16x16x32_bf16 v[2:5], v[180:183], v[212:215], v[2:5]
	s_barrier
	s_cbranch_scc0 .LBB0_1325
	s_and_b64 vcc, exec, s[10:11]
	s_cbranch_vccz .LBB0_1328
	s_barrier
